# split + remap + nt hint on the non-halo LayerNorm row loads/stores of phases 7 and 15
# baseline (speedup 1.0000x reference)
;     ...
;     if (p0 < p1) {
; #pragma unroll
;         for (int r = 0; r < NR; ++r) { const bf16_t* p = z + (size_t)rowr(p0, r) * DM;
; #pragma unroll
;             for (int j = 0; j < 2; ++j) raw[r][j] = *(const pg8::u32x4*)(p + 8 * lane + 512 * j); } }
;     for (int pi = p0; pi < p1; pi += NP * pstep) {
;         int row[NR];
; #pragma unroll
;         for (int r = 0; r < NR; ++r) row[r] = rowr(pi, r);
;         f32x4 v[NR][4]; float s[NR];
; #pragma unroll
;         for (int r = 0; r < NR; ++r) { s[r] = 0.f;
; #pragma unroll
;             for (int j = 0; j < 2; ++j) {
;                 v[r][2 * j][0] = __builtin_bit_cast(float, raw[r][j].x << 16); v[r][2 * j][1] = __builtin_bit_cast(float, raw[r][j].x & 0xffff0000u);
;                 v[r][2 * j][2] = __builtin_bit_cast(float, raw[r][j].y << 16); v[r][2 * j][3] = __builtin_bit_cast(float, raw[r][j].y & 0xffff0000u);
;                 v[r][2 * j + 1][0] = __builtin_bit_cast(float, raw[r][j].z << 16); v[r][2 * j + 1][1] = __builtin_bit_cast(float, raw[r][j].z & 0xffff0000u);
;                 v[r][2 * j + 1][2] = __builtin_bit_cast(float, raw[r][j].w << 16); v[r][2 * j + 1][3] = __builtin_bit_cast(float, raw[r][j].w & 0xffff0000u); } }
;         { const int nxt = pi + NP * pstep, pq = nxt < p1 ? nxt : pi;
; #pragma unroll
;           for (int r = 0; r < NR; ++r) { const bf16_t* pn = z + (size_t)rowr(pq, r) * DM;
; #pragma unroll
;               for (int j = 0; j < 2; ++j) raw[r][j] = *(const pg8::u32x4*)(pn + 8 * lane + 512 * j); } }
; #pragma unroll
;         for (int r = 0; r < NR; ++r)
; #pragma unroll
;             for (int j = 0; j < 4; ++j) s[r] += (v[r][j][0] + v[r][j][1]) + (v[r][j][2] + v[r][j][3]);
;         float mean[NR], q[NR], rstd[NR];
; #pragma unroll
;         for (int r = 0; r < NR; ++r) { mean[r] = wave_sum_dpp(s[r]) * (1.f / DM); q[r] = 0.f;
; #pragma unroll
;             for (int j = 0; j < 4; ++j) { v[r][j] = v[r][j] - mean[r]; q[r] += (v[r][j][0] * v[r][j][0] + v[r][j][1] * v[r][j][1]) + (v[r][j][2] * v[r][j][2] + v[r][j][3] * v[r][j][3]); } }
; #pragma unroll
;         for (int r = 0; r < NR; ++r) rstd[r] = 1.0f / sqrtf(wave_sum_dpp(q[r]) * (1.f / DM) + 1e-5f);
;         if (MODE == 1) {
; #pragma unroll
;             for (int r = 0; r < NR; ++r) if (lane == r) { stats[2 * row[r]] = mean[r]; stats[2 * row[r] + 1] = rstd[r]; } }
; #pragma unroll
;         for (int j = 0; j < 2; ++j) {
.LBB0_687:
	v_readlane_b32 s0, v253, 20
	s_add_i32 s3, s38, s0
	s_and_b64 vcc, exec, s[6:7]
	s_cbranch_vccz .LBB0_707
	s_add_i32 s20, s3, 0xfffffd40
	s_cmpk_gt_i32 s20, 0x3dff
	s_cbranch_scc1 .LBB0_707
	v_readlane_b32 s0, v253, 4
	v_readlane_b32 s1, v253, 5
	s_load_dwordx4 s[8:11], s[0:1], 0xa8
	v_readlane_b32 s0, v253, 27
	s_add_i32 s21, s0, 0xfffffd40
	v_readlane_b32 s0, v253, 21
	s_waitcnt vmcnt(0)
	v_lshlrev_b32_e32 v70, 4, v145
	v_mov_b32_e32 v71, 0
	v_readlane_b32 s1, v253, 22
	v_lshlrev_b32_e32 v68, 5, v145
	v_mov_b32_e32 v147, 0x3727c5ac
	v_lshl_add_u64 v[66:67], s[0:1], 0, v[70:71]
	s_mul_hi_i32 s0, s20, 0x84210843
	s_add_i32 s0, s0, s20
	s_lshr_b32 s1, s0, 31
	s_ashr_i32 s0, s0, 4
	s_add_i32 s0, s0, s1
	s_add_i32 s0, s0, s20
	s_lshl_b32 s0, s0, 1
	s_ashr_i32 s1, s0, 31
	s_lshl_b64 s[4:5], s[0:1], 11
	s_or_b32 s0, s0, 1
	s_ashr_i32 s1, s0, 31
	v_lshl_add_u64 v[2:3], v[66:67], 0, s[4:5]
	s_lshl_b64 s[0:1], s[0:1], 11
	global_load_dwordx4 v[46:49], v[2:3], off nt
	global_load_dwordx4 v[50:53], v[2:3], off offset:1024 nt
	v_lshl_add_u64 v[2:3], v[66:67], 0, s[0:1]
	s_add_i32 s0, s20, s21
	s_cmpk_lt_i32 s0, 0x3e00
	s_cselect_b32 s0, s0, s20
	s_mul_hi_i32 s1, s0, 0x84210843
	s_add_i32 s1, s1, s0
	s_lshr_b32 s2, s1, 31
	s_ashr_i32 s1, s1, 4
	s_add_i32 s1, s1, s2
	s_add_i32 s1, s1, s0
	s_lshl_b32 s0, s1, 1
	s_ashr_i32 s1, s0, 31
	s_lshl_b64 s[4:5], s[0:1], 11
	s_or_b32 s0, s0, 1
	s_ashr_i32 s1, s0, 31
	global_load_dwordx4 v[38:41], v[2:3], off nt
	global_load_dwordx4 v[54:57], v[2:3], off offset:1024 nt
	v_lshl_add_u64 v[2:3], v[66:67], 0, s[4:5]
	s_lshl_b64 s[0:1], s[0:1], 11
	global_load_dwordx4 v[34:37], v[2:3], off nt
	global_load_dwordx4 v[58:61], v[2:3], off offset:1024 nt
	v_lshl_add_u64 v[2:3], v[66:67], 0, s[0:1]
	global_load_dwordx4 v[42:45], v[2:3], off nt
	global_load_dwordx4 v[62:65], v[2:3], off offset:1024 nt
	s_waitcnt lgkmcnt(0)
	global_load_dwordx4 v[2:5], v68, s[8:9] offset:16
	global_load_dwordx4 v[6:9], v68, s[10:11] offset:16
	global_load_dwordx4 v[10:13], v68, s[8:9]
	global_load_dwordx4 v[14:17], v68, s[10:11]
	global_load_dwordx4 v[18:21], v68, s[8:9] offset:2064
	global_load_dwordx4 v[22:25], v68, s[10:11] offset:2064
	global_load_dwordx4 v[26:29], v68, s[8:9] offset:2048
	global_load_dwordx4 v[30:33], v68, s[10:11] offset:2048
	v_readlane_b32 s0, v253, 23
	v_readlane_b32 s1, v253, 24
	s_mov_b32 s26, 0xf800000
	v_mov_b32_e32 v150, 0x260
	v_lshl_add_u64 v[68:69], s[0:1], 0, v[70:71]
	v_or_b32_e32 v70, 0x400, v70
	v_lshl_add_u64 v[70:71], s[0:1], 0, v[70:71]
	s_branch .LBB0_691
.LBB0_690:
	s_or_b64 exec, exec, s[22:23]
	v_pk_mul_f32 v[106:107], v[106:107], v[142:143] op_sel_hi:[1,0]
	v_pk_mul_f32 v[104:105], v[104:105], v[142:143] op_sel_hi:[1,0]
	v_pk_mul_f32 v[110:111], v[110:111], v[142:143] op_sel_hi:[1,0]
	v_pk_mul_f32 v[108:109], v[108:109], v[142:143] op_sel_hi:[1,0]
	s_ashr_i32 s9, s8, 31
	s_waitcnt vmcnt(12)
	v_pk_fma_f32 v[106:107], v[12:13], v[106:107], v[16:17]
	v_pk_fma_f32 v[104:105], v[10:11], v[104:105], v[14:15]
	v_pk_fma_f32 v[110:111], v[4:5], v[110:111], v[8:9]
	v_pk_fma_f32 v[108:109], v[2:3], v[108:109], v[6:7]
	s_lshl_b64 s[8:9], s[8:9], 11
	v_cvt_pk_bf16_f32 v104, v104, v105
	v_cvt_pk_bf16_f32 v105, v106, v107
	v_cvt_pk_bf16_f32 v106, v108, v109
	v_cvt_pk_bf16_f32 v107, v110, v111
	v_lshl_add_u64 v[108:109], v[68:69], 0, s[8:9]
	global_store_dwordx4 v[108:109], v[104:107], off nt
	v_pk_mul_f32 v[110:111], v[118:119], v[140:141] op_sel_hi:[1,0]
	s_ashr_i32 s7, s6, 31
	v_pk_mul_f32 v[104:105], v[116:117], v[140:141] op_sel_hi:[1,0]
	v_pk_mul_f32 v[106:107], v[114:115], v[140:141] op_sel_hi:[1,0]
	v_pk_fma_f32 v[108:109], v[12:13], v[104:105], v[16:17]
	v_pk_fma_f32 v[104:105], v[10:11], v[106:107], v[14:15]
	v_pk_mul_f32 v[106:107], v[120:121], v[140:141] op_sel_hi:[1,0]
	s_lshl_b64 s[6:7], s[6:7], 11
	v_pk_fma_f32 v[112:113], v[4:5], v[106:107], v[8:9]
	v_pk_fma_f32 v[106:107], v[2:3], v[110:111], v[6:7]
	v_cvt_pk_bf16_f32 v104, v104, v105
	v_cvt_pk_bf16_f32 v105, v108, v109
	v_cvt_pk_bf16_f32 v106, v106, v107
	v_cvt_pk_bf16_f32 v107, v112, v113
	v_lshl_add_u64 v[108:109], v[68:69], 0, s[6:7]
	global_store_dwordx4 v[108:109], v[104:107], off nt
	v_pk_mul_f32 v[110:111], v[126:127], v[146:147] op_sel_hi:[1,0]
	s_ashr_i32 s13, s12, 31
	v_pk_mul_f32 v[104:105], v[124:125], v[146:147] op_sel_hi:[1,0]
	v_pk_mul_f32 v[106:107], v[122:123], v[146:147] op_sel_hi:[1,0]
	v_pk_fma_f32 v[108:109], v[12:13], v[104:105], v[16:17]
	v_pk_fma_f32 v[104:105], v[10:11], v[106:107], v[14:15]
	v_pk_mul_f32 v[106:107], v[128:129], v[146:147] op_sel_hi:[1,0]
	s_lshl_b64 s[12:13], s[12:13], 11
	v_pk_fma_f32 v[112:113], v[4:5], v[106:107], v[8:9]
	v_pk_fma_f32 v[106:107], v[2:3], v[110:111], v[6:7]
	v_cvt_pk_bf16_f32 v104, v104, v105
	v_cvt_pk_bf16_f32 v105, v108, v109
	v_cvt_pk_bf16_f32 v106, v106, v107
	v_cvt_pk_bf16_f32 v107, v112, v113
	v_lshl_add_u64 v[108:109], v[68:69], 0, s[12:13]
	global_store_dwordx4 v[108:109], v[104:107], off nt
	s_add_i32 s0, s20, s21
	v_pk_mul_f32 v[110:111], v[134:135], v[144:145] op_sel_hi:[1,0]
	v_pk_mul_f32 v[104:105], v[132:133], v[144:145] op_sel_hi:[1,0]
	v_pk_mul_f32 v[106:107], v[130:131], v[144:145] op_sel_hi:[1,0]
	v_pk_fma_f32 v[108:109], v[12:13], v[104:105], v[16:17]
	v_pk_fma_f32 v[104:105], v[10:11], v[106:107], v[14:15]
	v_pk_mul_f32 v[106:107], v[136:137], v[144:145] op_sel_hi:[1,0]
	s_ashr_i32 s11, s10, 31
	s_add_i32 s20, s0, s21
	v_pk_fma_f32 v[112:113], v[4:5], v[106:107], v[8:9]
	v_pk_fma_f32 v[106:107], v[2:3], v[110:111], v[6:7]
	s_lshl_b64 s[0:1], s[10:11], 11
	v_cvt_pk_bf16_f32 v104, v104, v105
	v_cvt_pk_bf16_f32 v105, v108, v109
	v_cvt_pk_bf16_f32 v106, v106, v107
	v_cvt_pk_bf16_f32 v107, v112, v113
	v_lshl_add_u64 v[108:109], v[68:69], 0, s[0:1]
	v_pk_mul_f32 v[102:103], v[102:103], v[142:143] op_sel_hi:[1,0]
	v_pk_mul_f32 v[100:101], v[100:101], v[142:143] op_sel_hi:[1,0]
	v_pk_mul_f32 v[98:99], v[98:99], v[142:143] op_sel_hi:[1,0]
	v_pk_mul_f32 v[96:97], v[96:97], v[142:143] op_sel_hi:[1,0]
	global_store_dwordx4 v[108:109], v[104:107], off nt
	s_waitcnt vmcnt(12)
;     ...
;         for (int r = 0; r < NR; ++r) { s[r] = 0.f;
; #pragma unroll
;             for (int j = 0; j < 2; ++j) {
;                 v[r][2 * j][0] = __builtin_bit_cast(float, raw[r][j].x << 16); v[r][2 * j][1] = __builtin_bit_cast(float, raw[r][j].x & 0xffff0000u);
;                 v[r][2 * j][2] = __builtin_bit_cast(float, raw[r][j].y << 16); v[r][2 * j][3] = __builtin_bit_cast(float, raw[r][j].y & 0xffff0000u);
;                 v[r][2 * j + 1][0] = __builtin_bit_cast(float, raw[r][j].z << 16); v[r][2 * j + 1][1] = __builtin_bit_cast(float, raw[r][j].z & 0xffff0000u);
;                 v[r][2 * j + 1][2] = __builtin_bit_cast(float, raw[r][j].w << 16); v[r][2 * j + 1][3] = __builtin_bit_cast(float, raw[r][j].w & 0xffff0000u); } }
;         { const int nxt = pi + NP * pstep, pq = nxt < p1 ? nxt : pi;
; #pragma unroll
;           for (int r = 0; r < NR; ++r) { const bf16_t* pn = z + (size_t)rowr(pq, r) * DM;
; #pragma unroll
;               for (int j = 0; j < 2; ++j) raw[r][j] = *(const pg8::u32x4*)(pn + 8 * lane + 512 * j); } }
; #pragma unroll
;         for (int r = 0; r < NR; ++r)
; #pragma unroll
;             for (int j = 0; j < 4; ++j) s[r] += (v[r][j][0] + v[r][j][1]) + (v[r][j][2] + v[r][j][3]);
;         float mean[NR], q[NR], rstd[NR];
; #pragma unroll
;         for (int r = 0; r < NR; ++r) { mean[r] = wave_sum_dpp(s[r]) * (1.f / DM); q[r] = 0.f;
; #pragma unroll
;             for (int j = 0; j < 4; ++j) { v[r][j] = v[r][j] - mean[r]; q[r] += (v[r][j][0] * v[r][j][0] + v[r][j][1] * v[r][j][1]) + (v[r][j][2] * v[r][j][2] + v[r][j][3] * v[r][j][3]); } }
; #pragma unroll
;         for (int r = 0; r < NR; ++r) rstd[r] = 1.0f / sqrtf(wave_sum_dpp(q[r]) * (1.f / DM) + 1e-5f);
;         if (MODE == 1) {
; #pragma unroll
;             for (int r = 0; r < NR; ++r) if (lane == r) { stats[2 * row[r]] = mean[r]; stats[2 * row[r] + 1] = rstd[r]; } }
; #pragma unroll
;         for (int j = 0; j < 2; ++j) {
;             const int c = 8 * lane + 512 * j;
;             const f32x4 g0 = *(const f32x4*)(g + c), g1 = *(const f32x4*)(g + c + 4), b0 = *(const f32x4*)(b + c), b1 = *(const f32x4*)(b + c + 4);
; #pragma unroll
;             for (int r = 0; r < NR; ++r) {
;                 const f32x4 o0 = v[r][2 * j] * rstd[r] * g0 + b0, o1 = v[r][2 * j + 1] * rstd[r] * g1 + b1;
	v_pk_fma_f32 v[102:103], v[28:29], v[102:103], v[32:33]
	v_pk_fma_f32 v[100:101], v[26:27], v[100:101], v[30:31]
	v_pk_fma_f32 v[104:105], v[20:21], v[98:99], v[24:25]
	v_pk_fma_f32 v[98:99], v[18:19], v[96:97], v[22:23]
	v_cvt_pk_bf16_f32 v96, v100, v101
	v_cvt_pk_bf16_f32 v97, v102, v103
	v_cvt_pk_bf16_f32 v98, v98, v99
	v_cvt_pk_bf16_f32 v99, v104, v105
	v_lshl_add_u64 v[100:101], v[70:71], 0, s[8:9]
	v_pk_mul_f32 v[94:95], v[94:95], v[140:141] op_sel_hi:[1,0]
	v_pk_mul_f32 v[90:91], v[90:91], v[140:141] op_sel_hi:[1,0]
	v_pk_mul_f32 v[92:93], v[92:93], v[140:141] op_sel_hi:[1,0]
	v_pk_mul_f32 v[88:89], v[88:89], v[140:141] op_sel_hi:[1,0]
	global_store_dwordx4 v[100:101], v[96:99], off nt
	v_pk_fma_f32 v[94:95], v[28:29], v[94:95], v[32:33]
	v_pk_fma_f32 v[90:91], v[26:27], v[90:91], v[30:31]
	v_pk_fma_f32 v[92:93], v[20:21], v[92:93], v[24:25]
	v_pk_fma_f32 v[96:97], v[18:19], v[88:89], v[22:23]
	v_cvt_pk_bf16_f32 v88, v90, v91
	v_cvt_pk_bf16_f32 v89, v94, v95
	v_cvt_pk_bf16_f32 v90, v96, v97
	v_cvt_pk_bf16_f32 v91, v92, v93
	v_lshl_add_u64 v[92:93], v[70:71], 0, s[6:7]
	v_pk_mul_f32 v[86:87], v[86:87], v[146:147] op_sel_hi:[1,0]
	v_pk_mul_f32 v[82:83], v[82:83], v[146:147] op_sel_hi:[1,0]
	v_pk_mul_f32 v[84:85], v[84:85], v[146:147] op_sel_hi:[1,0]
	v_pk_mul_f32 v[80:81], v[80:81], v[146:147] op_sel_hi:[1,0]
	global_store_dwordx4 v[92:93], v[88:91], off nt
	v_pk_fma_f32 v[86:87], v[28:29], v[86:87], v[32:33]
	v_pk_fma_f32 v[82:83], v[26:27], v[82:83], v[30:31]
	v_pk_fma_f32 v[84:85], v[20:21], v[84:85], v[24:25]
	v_pk_fma_f32 v[88:89], v[18:19], v[80:81], v[22:23]
	v_cvt_pk_bf16_f32 v80, v82, v83
	v_cvt_pk_bf16_f32 v81, v86, v87
	v_cvt_pk_bf16_f32 v82, v88, v89
	v_cvt_pk_bf16_f32 v83, v84, v85
	v_lshl_add_u64 v[84:85], v[70:71], 0, s[12:13]
	v_pk_mul_f32 v[78:79], v[78:79], v[144:145] op_sel_hi:[1,0]
	v_pk_mul_f32 v[74:75], v[74:75], v[144:145] op_sel_hi:[1,0]
	v_pk_mul_f32 v[76:77], v[76:77], v[144:145] op_sel_hi:[1,0]
	v_pk_mul_f32 v[72:73], v[72:73], v[144:145] op_sel_hi:[1,0]
	global_store_dwordx4 v[84:85], v[80:83], off nt
	v_pk_fma_f32 v[78:79], v[28:29], v[78:79], v[32:33]
	v_pk_fma_f32 v[74:75], v[26:27], v[74:75], v[30:31]
	v_pk_fma_f32 v[76:77], v[20:21], v[76:77], v[24:25]
	v_pk_fma_f32 v[80:81], v[18:19], v[72:73], v[22:23]
	v_cvt_pk_bf16_f32 v72, v74, v75
	v_cvt_pk_bf16_f32 v73, v78, v79
	v_cvt_pk_bf16_f32 v74, v80, v81
	v_cvt_pk_bf16_f32 v75, v76, v77
	v_lshl_add_u64 v[76:77], v[70:71], 0, s[0:1]
	s_cmpk_gt_i32 s20, 0x3dff
	global_store_dwordx4 v[76:77], v[72:75], off nt
	s_cbranch_scc1 .LBB0_707
.LBB0_691:
	s_waitcnt vmcnt(14)
	v_lshlrev_b32_e32 v100, 16, v50
	v_and_b32_e32 v101, 0xffff0000, v50
	v_lshlrev_b32_e32 v96, 16, v52
	v_and_b32_e32 v116, 0xffff0000, v52
	s_waitcnt vmcnt(8)
	v_lshlrev_b32_e32 v74, 16, v62
	v_and_b32_e32 v75, 0xffff0000, v62
	v_lshlrev_b32_e32 v78, 16, v63
	v_and_b32_e32 v79, 0xffff0000, v63
	v_lshlrev_b32_e32 v72, 16, v64
	v_and_b32_e32 v52, 0xffff0000, v64
	v_lshlrev_b32_e32 v76, 16, v65
	v_and_b32_e32 v50, 0xffff0000, v65
	v_lshlrev_b32_e32 v63, 16, v47
	v_lshlrev_b32_e32 v62, 16, v46
	v_and_b32_e32 v65, 0xffff0000, v47
	v_and_b32_e32 v64, 0xffff0000, v46
	v_pk_add_f32 v[46:47], v[62:63], v[64:65]
	v_lshlrev_b32_e32 v119, 16, v49
	v_add_f32_e32 v46, v46, v47
	v_lshlrev_b32_e32 v118, 16, v48
	v_and_b32_e32 v121, 0xffff0000, v49
	v_and_b32_e32 v120, 0xffff0000, v48
	v_add_f32_e32 v115, 0, v46
	v_pk_add_f32 v[46:47], v[118:119], v[120:121]
	v_lshlrev_b32_e32 v102, 16, v51
	v_and_b32_e32 v103, 0xffff0000, v51
	v_pk_add_f32 v[46:47], v[46:47], v[46:47] op_sel_hi:[0,1]
	v_lshlrev_b32_e32 v98, 16, v53
	v_and_b32_e32 v114, 0xffff0000, v53
	v_add_f32_e32 v97, v100, v101
	v_add_f32_e32 v117, v102, v103
	v_mov_b32_e32 v99, v47
	v_lshlrev_b32_e32 v127, 16, v39
	v_lshlrev_b32_e32 v126, 16, v38
	v_and_b32_e32 v129, 0xffff0000, v39
	v_and_b32_e32 v128, 0xffff0000, v38
	v_lshlrev_b32_e32 v90, 16, v54
	v_and_b32_e32 v91, 0xffff0000, v54
	v_lshlrev_b32_e32 v88, 16, v56
	v_and_b32_e32 v124, 0xffff0000, v56
	v_lshlrev_b32_e32 v82, 16, v58
	v_and_b32_e32 v83, 0xffff0000, v58
	v_lshlrev_b32_e32 v86, 16, v59
	v_and_b32_e32 v87, 0xffff0000, v59
	v_lshlrev_b32_e32 v80, 16, v60
	v_and_b32_e32 v56, 0xffff0000, v60
	v_lshlrev_b32_e32 v84, 16, v61
	v_and_b32_e32 v54, 0xffff0000, v61
	v_pk_add_f32 v[48:49], v[96:97], v[116:117]
	v_pk_add_f32 v[46:47], v[98:99], v[114:115]
	v_pk_add_f32 v[38:39], v[126:127], v[128:129]
	v_lshlrev_b32_e32 v59, 16, v35
	v_lshlrev_b32_e32 v58, 16, v34
	v_and_b32_e32 v61, 0xffff0000, v35
	v_and_b32_e32 v60, 0xffff0000, v34
	v_pk_add_f32 v[46:47], v[48:49], v[46:47]
	v_add_f32_e32 v38, v38, v39
	v_lshlrev_b32_e32 v131, 16, v41
	v_lshlrev_b32_e32 v130, 16, v40
	v_and_b32_e32 v133, 0xffff0000, v41
	v_and_b32_e32 v132, 0xffff0000, v40
	v_pk_add_f32 v[34:35], v[58:59], v[60:61]
	v_add_f32_e32 v97, v46, v47
	v_add_f32_e32 v123, 0, v38
	v_pk_add_f32 v[38:39], v[130:131], v[132:133]
	v_add_f32_e32 v34, v34, v35
	v_lshlrev_b32_e32 v47, 16, v37
	v_lshlrev_b32_e32 v46, 16, v36
	v_and_b32_e32 v49, 0xffff0000, v37
	v_and_b32_e32 v48, 0xffff0000, v36
	v_lshlrev_b32_e32 v94, 16, v55
	v_and_b32_e32 v95, 0xffff0000, v55
	v_pk_add_f32 v[38:39], v[38:39], v[38:39] op_sel_hi:[0,1]
	v_add_f32_e32 v55, 0, v34
	v_pk_add_f32 v[34:35], v[46:47], v[48:49]
	v_lshlrev_b32_e32 v92, 16, v57
	v_and_b32_e32 v122, 0xffff0000, v57
	v_add_f32_e32 v89, v90, v91
	v_add_f32_e32 v125, v94, v95
	v_mov_b32_e32 v93, v39
	v_pk_add_f32 v[34:35], v[34:35], v[34:35] op_sel_hi:[0,1]
	v_pk_add_f32 v[40:41], v[88:89], v[124:125]
	v_pk_add_f32 v[38:39], v[92:93], v[122:123]
	v_add_f32_e32 v81, v82, v83
	v_add_f32_e32 v57, v86, v87
; template <int CTRL> __device__ __forceinline__ float dpp_mov(float x) { return __builtin_bit_cast(float, __builtin_amdgcn_update_dpp(0, __builtin_bit_cast(int, x), CTRL, 0xF, 0xF, true)); }
; __device__ __forceinline__ float rowsum16(float x) { x += dpp_mov<0x128>(x); x += dpp_mov<0x124>(x); x += dpp_mov<0x122>(x); x += dpp_mov<0x121>(x); return x; }
; __device__ __forceinline__ float rl(float x, int l) { return __builtin_bit_cast(float, __builtin_amdgcn_readlane(__builtin_bit_cast(int, x), l)); }
; __device__ __forceinline__ float wave_sum_dpp(float x) { x = rowsum16(x); return (rl(x, 0) + rl(x, 16)) + (rl(x, 32) + rl(x, 48)); }
;     ...
;             for (int j = 0; j < 4; ++j) s[r] += (v[r][j][0] + v[r][j][1]) + (v[r][j][2] + v[r][j][3]);
;         float mean[NR], q[NR], rstd[NR];
; #pragma unroll
;         for (int r = 0; r < NR; ++r) { mean[r] = wave_sum_dpp(s[r]) * (1.f / DM); q[r] = 0.f;
; #pragma unroll
;             for (int j = 0; j < 4; ++j) { v[r][j] = v[r][j] - mean[r]; q[r] += (v[r][j][0] * v[r][j][0] + v[r][j][1] * v[r][j][1]) + (v[r][j][2] * v[r][j][2] + v[r][j][3] * v[r][j][3]); } }
; #pragma unroll
;         for (int r = 0; r < NR; ++r) rstd[r] = 1.0f / sqrtf(wave_sum_dpp(q[r]) * (1.f / DM) + 1e-5f);
	v_mov_b32_e32 v85, v35
	v_pk_add_f32 v[38:39], v[40:41], v[38:39]
	v_pk_add_f32 v[36:37], v[80:81], v[56:57]
	v_pk_add_f32 v[34:35], v[84:85], v[54:55]
	v_add_f32_e32 v89, v38, v39
	v_pk_add_f32 v[34:35], v[36:37], v[34:35]
	v_lshlrev_b32_e32 v39, 16, v43
	v_lshlrev_b32_e32 v38, 16, v42
	v_and_b32_e32 v41, 0xffff0000, v43
	v_and_b32_e32 v40, 0xffff0000, v42
	v_add_f32_e32 v55, v34, v35
	v_pk_add_f32 v[34:35], v[38:39], v[40:41]
	v_and_b32_e32 v37, 0xffff0000, v45
	v_add_f32_e32 v34, v34, v35
	v_add_f32_e32 v51, 0, v34
	v_lshlrev_b32_e32 v35, 16, v45
	v_lshlrev_b32_e32 v34, 16, v44
	v_and_b32_e32 v36, 0xffff0000, v44
	v_pk_add_f32 v[42:43], v[34:35], v[36:37]
	v_add_f32_e32 v73, v74, v75
	v_pk_add_f32 v[42:43], v[42:43], v[42:43] op_sel_hi:[0,1]
	v_add_f32_e32 v53, v78, v79
	v_mov_b32_e32 v77, v43
	v_pk_add_f32 v[44:45], v[72:73], v[52:53]
	v_pk_add_f32 v[42:43], v[76:77], v[50:51]
	s_nop 0
	v_pk_add_f32 v[42:43], v[44:45], v[42:43]
	s_nop 0
	v_add_f32_e32 v44, v42, v43
	v_add_f32_dpp v42, v97, v97 row_ror:8 row_mask:0xf bank_mask:0xf bound_ctrl:1
	s_nop 1
	v_add_f32_dpp v42, v42, v42 row_ror:4 row_mask:0xf bank_mask:0xf bound_ctrl:1
	s_nop 1
	v_add_f32_dpp v42, v42, v42 row_ror:2 row_mask:0xf bank_mask:0xf bound_ctrl:1
	s_nop 1
	v_add_f32_dpp v42, v42, v42 row_ror:1 row_mask:0xf bank_mask:0xf bound_ctrl:1
	s_nop 0
	v_readlane_b32 s2, v42, 16
	v_readlane_b32 s4, v42, 48
	v_readlane_b32 s0, v42, 0
	v_readlane_b32 s1, v42, 32
	v_mov_b32_e32 v42, s2
	v_mov_b32_e32 v43, s4
	v_pk_add_f32 v[42:43], s[0:1], v[42:43]
	s_nop 0
	v_add_f32_e32 v42, v42, v43
	v_fmac_f32_e32 v65, 0xba800000, v42
	v_fmac_f32_e32 v64, 0xba800000, v42
	v_fmac_f32_e32 v63, 0xba800000, v42
	v_fmac_f32_e32 v62, 0xba800000, v42
	v_mul_f32_e32 v43, v64, v64
	v_mul_f32_e32 v45, v65, v65
	v_fmac_f32_e32 v43, v62, v62
	v_fmac_f32_e32 v45, v63, v63
	v_fmac_f32_e32 v121, 0xba800000, v42
	v_fmac_f32_e32 v120, 0xba800000, v42
	v_add_f32_e32 v43, v43, v45
	v_fmac_f32_e32 v119, 0xba800000, v42
	v_fmac_f32_e32 v118, 0xba800000, v42
	v_mul_f32_e32 v45, v120, v120
	v_mul_f32_e32 v51, v121, v121
	v_fmac_f32_e32 v45, v118, v118
	v_fmac_f32_e32 v51, v119, v119
	v_add_f32_e32 v45, v45, v51
	v_fmac_f32_e32 v103, 0xba800000, v42
	v_fmac_f32_e32 v101, 0xba800000, v42
	v_add_f32_e32 v43, v43, v45
	v_fmac_f32_e32 v102, 0xba800000, v42
	v_fmac_f32_e32 v100, 0xba800000, v42
	v_mul_f32_e32 v45, v101, v101
	v_mul_f32_e32 v51, v103, v103
	v_fmac_f32_e32 v45, v100, v100
	v_fmac_f32_e32 v51, v102, v102
	v_add_f32_e32 v45, v45, v51
	v_fmac_f32_e32 v114, 0xba800000, v42
	v_fmac_f32_e32 v116, 0xba800000, v42
	v_mul_f32_e32 v112, 0x3a800000, v42
	v_add_f32_e32 v43, v45, v43
	v_fmac_f32_e32 v98, 0xba800000, v42
	v_fmac_f32_e32 v96, 0xba800000, v42
	v_mul_f32_e32 v42, v116, v116
	v_mul_f32_e32 v45, v114, v114
	v_fmac_f32_e32 v42, v96, v96
	v_fmac_f32_e32 v45, v98, v98
	v_add_f32_e32 v42, v42, v45
	v_add_f32_e32 v45, v42, v43
	v_mov_b32_e32 v97, v116
	v_add_f32_dpp v42, v89, v89 row_ror:8 row_mask:0xf bank_mask:0xf bound_ctrl:1
	v_mov_b32_e32 v99, v114
	v_mov_b32_e32 v109, v120
	v_add_f32_dpp v42, v42, v42 row_ror:4 row_mask:0xf bank_mask:0xf bound_ctrl:1
	v_mov_b32_e32 v108, v118
	v_mov_b32_e32 v110, v119
	v_add_f32_dpp v42, v42, v42 row_ror:2 row_mask:0xf bank_mask:0xf bound_ctrl:1
	v_mov_b32_e32 v111, v121
	v_mov_b32_e32 v104, v62
	v_add_f32_dpp v42, v42, v42 row_ror:1 row_mask:0xf bank_mask:0xf bound_ctrl:1
	v_mov_b32_e32 v106, v63
	v_readlane_b32 s2, v42, 16
	v_readlane_b32 s4, v42, 48
	v_readlane_b32 s0, v42, 0
	v_readlane_b32 s1, v42, 32
	v_mov_b32_e32 v42, s2
	v_mov_b32_e32 v43, s4
	v_pk_add_f32 v[42:43], s[0:1], v[42:43]
	v_mov_b32_e32 v105, v64
	v_add_f32_e32 v42, v42, v43
	v_fmac_f32_e32 v129, 0xba800000, v42
	v_fmac_f32_e32 v128, 0xba800000, v42
	v_fmac_f32_e32 v127, 0xba800000, v42
	v_fmac_f32_e32 v126, 0xba800000, v42
	v_mul_f32_e32 v43, v128, v128
	v_mul_f32_e32 v51, v129, v129
	v_fmac_f32_e32 v43, v126, v126
	v_fmac_f32_e32 v51, v127, v127
	v_fmac_f32_e32 v133, 0xba800000, v42
	v_fmac_f32_e32 v132, 0xba800000, v42
	v_add_f32_e32 v43, v43, v51
	v_fmac_f32_e32 v131, 0xba800000, v42
	v_fmac_f32_e32 v130, 0xba800000, v42
	v_mul_f32_e32 v51, v132, v132
	v_mul_f32_e32 v53, v133, v133
	v_fmac_f32_e32 v51, v130, v130
	v_fmac_f32_e32 v53, v131, v131
	v_add_f32_e32 v51, v51, v53
	v_fmac_f32_e32 v95, 0xba800000, v42
	v_fmac_f32_e32 v91, 0xba800000, v42
	v_add_f32_e32 v43, v43, v51
	v_fmac_f32_e32 v94, 0xba800000, v42
	v_fmac_f32_e32 v90, 0xba800000, v42
	v_mul_f32_e32 v51, v91, v91
	v_mul_f32_e32 v53, v95, v95
	v_fmac_f32_e32 v51, v90, v90
	v_fmac_f32_e32 v53, v94, v94
	v_add_f32_e32 v51, v51, v53
	v_fmac_f32_e32 v122, 0xba800000, v42
	v_fmac_f32_e32 v124, 0xba800000, v42
	v_mul_f32_e32 v138, 0x3a800000, v42
	v_add_f32_e32 v43, v51, v43
	v_fmac_f32_e32 v92, 0xba800000, v42
	v_fmac_f32_e32 v88, 0xba800000, v42
	v_mul_f32_e32 v42, v124, v124
	v_mul_f32_e32 v51, v122, v122
	v_fmac_f32_e32 v42, v88, v88
	v_fmac_f32_e32 v51, v92, v92
	v_add_f32_e32 v42, v42, v51
	v_add_f32_e32 v51, v42, v43
	v_mov_b32_e32 v116, v127
	v_add_f32_dpp v42, v55, v55 row_ror:8 row_mask:0xf bank_mask:0xf bound_ctrl:1
	v_mov_b32_e32 v114, v126
	v_mov_b32_e32 v115, v128
	v_add_f32_dpp v42, v42, v42 row_ror:4 row_mask:0xf bank_mask:0xf bound_ctrl:1
	v_mov_b32_e32 v120, v131
	v_mov_b32_e32 v118, v130
	v_add_f32_dpp v42, v42, v42 row_ror:2 row_mask:0xf bank_mask:0xf bound_ctrl:1
	v_mov_b32_e32 v117, v129
	v_mov_b32_e32 v119, v132
	v_add_f32_dpp v42, v42, v42 row_ror:1 row_mask:0xf bank_mask:0xf bound_ctrl:1
	v_mov_b32_e32 v121, v133
	v_readlane_b32 s2, v42, 16
	v_readlane_b32 s4, v42, 48
	v_readlane_b32 s0, v42, 0
	v_readlane_b32 s1, v42, 32
; __device__ __forceinline__ float wave_sum_dpp(float x) { x = rowsum16(x); return (rl(x, 0) + rl(x, 16)) + (rl(x, 32) + rl(x, 48)); }
;     ...
;         { const int nxt = pi + NP * pstep, pq = nxt < p1 ? nxt : pi;
; #pragma unroll
;           for (int r = 0; r < NR; ++r) { const bf16_t* pn = z + (size_t)rowr(pq, r) * DM;
; #pragma unroll
;               for (int j = 0; j < 2; ++j) raw[r][j] = *(const pg8::u32x4*)(pn + 8 * lane + 512 * j); } }
;     ...
;             for (int j = 0; j < 4; ++j) s[r] += (v[r][j][0] + v[r][j][1]) + (v[r][j][2] + v[r][j][3]);
;         float mean[NR], q[NR], rstd[NR];
; #pragma unroll
;         for (int r = 0; r < NR; ++r) { mean[r] = wave_sum_dpp(s[r]) * (1.f / DM); q[r] = 0.f;
; #pragma unroll
;             for (int j = 0; j < 4; ++j) { v[r][j] = v[r][j] - mean[r]; q[r] += (v[r][j][0] * v[r][j][0] + v[r][j][1] * v[r][j][1]) + (v[r][j][2] * v[r][j][2] + v[r][j][3] * v[r][j][3]); } }
; #pragma unroll
;         for (int r = 0; r < NR; ++r) rstd[r] = 1.0f / sqrtf(wave_sum_dpp(q[r]) * (1.f / DM) + 1e-5f);
	v_mov_b32_e32 v42, s2
	v_mov_b32_e32 v43, s4
	v_pk_add_f32 v[42:43], s[0:1], v[42:43]
	v_mov_b32_e32 v89, v124
	v_add_f32_e32 v42, v42, v43
	v_fmac_f32_e32 v48, 0xba800000, v42
	v_fmac_f32_e32 v61, 0xba800000, v42
	v_fmac_f32_e32 v60, 0xba800000, v42
	v_fmac_f32_e32 v49, 0xba800000, v42
	v_fmac_f32_e32 v46, 0xba800000, v42
	v_mov_b32_e32 v127, v48
	v_mul_f32_e32 v48, v48, v48
	v_fmac_f32_e32 v59, 0xba800000, v42
	v_fmac_f32_e32 v58, 0xba800000, v42
	v_mul_f32_e32 v43, v60, v60
	v_mul_f32_e32 v53, v61, v61
	v_fmac_f32_e32 v47, 0xba800000, v42
	v_mov_b32_e32 v126, v46
	v_fmac_f32_e32 v48, v46, v46
	v_mul_f32_e32 v46, v49, v49
	v_fmac_f32_e32 v43, v58, v58
	v_fmac_f32_e32 v53, v59, v59
	v_fmac_f32_e32 v46, v47, v47
	v_add_f32_e32 v43, v43, v53
	v_add_f32_e32 v46, v48, v46
	v_fmac_f32_e32 v87, 0xba800000, v42
	v_fmac_f32_e32 v83, 0xba800000, v42
	v_mov_b32_e32 v128, v47
	v_add_f32_e32 v43, v43, v46
	v_fmac_f32_e32 v86, 0xba800000, v42
	v_fmac_f32_e32 v82, 0xba800000, v42
	v_mul_f32_e32 v46, v83, v83
	v_mul_f32_e32 v47, v87, v87
	v_fmac_f32_e32 v46, v82, v82
	v_fmac_f32_e32 v47, v86, v86
	v_add_f32_e32 v46, v46, v47
	v_fmac_f32_e32 v54, 0xba800000, v42
	v_fmac_f32_e32 v56, 0xba800000, v42
	v_mul_f32_e32 v140, 0x3a800000, v42
	v_add_f32_e32 v43, v46, v43
	v_fmac_f32_e32 v84, 0xba800000, v42
	v_fmac_f32_e32 v80, 0xba800000, v42
	v_mul_f32_e32 v42, v56, v56
	v_mul_f32_e32 v46, v54, v54
	v_fmac_f32_e32 v42, v80, v80
	v_fmac_f32_e32 v46, v84, v84
	v_add_f32_e32 v42, v42, v46
	v_add_f32_e32 v46, v42, v43
	v_mov_b32_e32 v129, v49
	v_add_f32_dpp v42, v44, v44 row_ror:8 row_mask:0xf bank_mask:0xf bound_ctrl:1
	v_mov_b32_e32 v93, v122
	v_mov_b32_e32 v122, v58
	v_add_f32_dpp v42, v42, v42 row_ror:4 row_mask:0xf bank_mask:0xf bound_ctrl:1
	v_mov_b32_e32 v123, v60
	v_mov_b32_e32 v124, v59
	v_add_f32_dpp v42, v42, v42 row_ror:2 row_mask:0xf bank_mask:0xf bound_ctrl:1
	v_mov_b32_e32 v125, v61
	v_mov_b32_e32 v81, v56
	v_add_f32_dpp v42, v42, v42 row_ror:1 row_mask:0xf bank_mask:0xf bound_ctrl:1
	v_mov_b32_e32 v85, v54
	v_readlane_b32 s2, v42, 16
	v_readlane_b32 s4, v42, 48
	v_readlane_b32 s0, v42, 0
	v_readlane_b32 s1, v42, 32
	v_mov_b32_e32 v42, s2
	v_mov_b32_e32 v43, s4
	v_pk_add_f32 v[42:43], s[0:1], v[42:43]
	v_readlane_b32 s1, v253, 27
	v_add_f32_e32 v42, v42, v43
	v_fmac_f32_e32 v36, 0xba800000, v42
	s_add_i32 s1, s1, s20
	v_fmac_f32_e32 v40, 0xba800000, v42
	v_fmac_f32_e32 v37, 0xba800000, v42
	v_fmac_f32_e32 v34, 0xba800000, v42
	v_mov_b32_e32 v135, v36
	v_mul_f32_e32 v36, v36, v36
	s_addk_i32 s1, 0xfd40
	v_fmac_f32_e32 v41, 0xba800000, v42
	v_fmac_f32_e32 v38, 0xba800000, v42
	v_mov_b32_e32 v131, v40
	v_mul_f32_e32 v40, v40, v40
	v_fmac_f32_e32 v35, 0xba800000, v42
	v_mov_b32_e32 v134, v34
	v_fmac_f32_e32 v36, v34, v34
	v_mul_f32_e32 v34, v37, v37
	s_cmpk_lt_i32 s1, 0x3e00
	v_fmac_f32_e32 v39, 0xba800000, v42
	v_mov_b32_e32 v130, v38
	v_fmac_f32_e32 v40, v38, v38
	v_mul_f32_e32 v38, v41, v41
	v_fmac_f32_e32 v34, v35, v35
	v_fmac_f32_e32 v79, 0xba800000, v42
	v_fmac_f32_e32 v75, 0xba800000, v42
	s_cselect_b32 s1, s1, s20
	v_fmac_f32_e32 v38, v39, v39
	v_mov_b32_e32 v136, v35
	v_add_f32_e32 v34, v36, v34
	v_fmac_f32_e32 v78, 0xba800000, v42
	v_fmac_f32_e32 v74, 0xba800000, v42
	v_mul_f32_e32 v35, v75, v75
	v_mul_f32_e32 v36, v79, v79
	s_mul_hi_i32 s10, s1, 0x84210843
	v_add_f32_e32 v38, v40, v38
	v_fmac_f32_e32 v35, v74, v74
	v_fmac_f32_e32 v36, v78, v78
	s_add_i32 s10, s10, s1
	v_add_f32_e32 v34, v38, v34
	v_add_f32_e32 v35, v35, v36
	v_fmac_f32_e32 v50, 0xba800000, v42
	v_fmac_f32_e32 v52, 0xba800000, v42
	s_lshr_b32 s12, s10, 31
	s_ashr_i32 s10, s10, 4
	v_add_f32_e32 v34, v35, v34
	v_fmac_f32_e32 v76, 0xba800000, v42
	v_fmac_f32_e32 v72, 0xba800000, v42
	v_mul_f32_e32 v35, v52, v52
	v_mul_f32_e32 v36, v50, v50
	s_add_i32 s10, s10, s12
	v_fmac_f32_e32 v35, v72, v72
	v_fmac_f32_e32 v36, v76, v76
	s_add_i32 s1, s10, s1
	v_add_f32_e32 v35, v35, v36
	s_lshl_b32 s12, s1, 1
	s_add_i32 s24, s55, s20
	v_add_f32_e32 v34, v35, v34
	v_add_f32_dpp v35, v45, v45 row_ror:8 row_mask:0xf bank_mask:0xf bound_ctrl:1
	s_or_b32 s10, s12, 1
	s_addk_i32 s24, 0xfa80
	v_add_f32_dpp v35, v35, v35 row_ror:4 row_mask:0xf bank_mask:0xf bound_ctrl:1
	s_cmpk_lt_i32 s24, 0x3e00
	s_cselect_b32 s27, s24, s20
	v_add_f32_dpp v35, v35, v35 row_ror:2 row_mask:0xf bank_mask:0xf bound_ctrl:1
	s_mul_hi_i32 s24, s27, 0x84210843
	s_add_i32 s24, s24, s27
	v_add_f32_dpp v35, v35, v35 row_ror:1 row_mask:0xf bank_mask:0xf bound_ctrl:1
	s_lshr_b32 s25, s24, 31
	v_readlane_b32 s6, v35, 0
	v_readlane_b32 s22, v35, 16
	v_readlane_b32 s7, v35, 32
	v_readlane_b32 s23, v35, 48
	v_add_f32_dpp v35, v51, v51 row_ror:8 row_mask:0xf bank_mask:0xf bound_ctrl:1
	s_ashr_i32 s24, s24, 4
	s_add_i32 s24, s24, s25
	v_add_f32_dpp v35, v35, v35 row_ror:4 row_mask:0xf bank_mask:0xf bound_ctrl:1
	s_add_i32 s24, s24, s27
	v_add_f32_dpp v34, v34, v34 row_ror:8 row_mask:0xf bank_mask:0xf bound_ctrl:1
	v_add_f32_dpp v35, v35, v35 row_ror:2 row_mask:0xf bank_mask:0xf bound_ctrl:1
	s_lshl_b32 s24, s24, 1
	v_add_f32_dpp v34, v34, v34 row_ror:4 row_mask:0xf bank_mask:0xf bound_ctrl:1
	v_add_f32_dpp v35, v35, v35 row_ror:1 row_mask:0xf bank_mask:0xf bound_ctrl:1
	s_ashr_i32 s25, s24, 31
	v_readlane_b32 s8, v35, 0
	v_readlane_b32 s18, v35, 16
	v_readlane_b32 s9, v35, 32
	v_readlane_b32 s19, v35, 48
	v_add_f32_dpp v35, v46, v46 row_ror:8 row_mask:0xf bank_mask:0xf bound_ctrl:1
	v_add_f32_dpp v34, v34, v34 row_ror:2 row_mask:0xf bank_mask:0xf bound_ctrl:1
	s_lshl_b64 s[28:29], s[24:25], 11
	v_add_f32_dpp v35, v35, v35 row_ror:4 row_mask:0xf bank_mask:0xf bound_ctrl:1
	s_or_b32 s24, s24, 1
; __device__ __forceinline__ float wave_sum_dpp(float x) { x = rowsum16(x); return (rl(x, 0) + rl(x, 16)) + (rl(x, 32) + rl(x, 48)); }
;     ...
;         { const int nxt = pi + NP * pstep, pq = nxt < p1 ? nxt : pi;
; #pragma unroll
;           for (int r = 0; r < NR; ++r) { const bf16_t* pn = z + (size_t)rowr(pq, r) * DM;
; #pragma unroll
;               for (int j = 0; j < 2; ++j) raw[r][j] = *(const pg8::u32x4*)(pn + 8 * lane + 512 * j); } }
; #pragma unroll
;         for (int r = 0; r < NR; ++r)
; #pragma unroll
;             for (int j = 0; j < 4; ++j) s[r] += (v[r][j][0] + v[r][j][1]) + (v[r][j][2] + v[r][j][3]);
;         float mean[NR], q[NR], rstd[NR];
; #pragma unroll
;         for (int r = 0; r < NR; ++r) { mean[r] = wave_sum_dpp(s[r]) * (1.f / DM); q[r] = 0.f;
; #pragma unroll
;             for (int j = 0; j < 4; ++j) { v[r][j] = v[r][j] - mean[r]; q[r] += (v[r][j][0] * v[r][j][0] + v[r][j][1] * v[r][j][1]) + (v[r][j][2] * v[r][j][2] + v[r][j][3] * v[r][j][3]); } }
; #pragma unroll
;         for (int r = 0; r < NR; ++r) rstd[r] = 1.0f / sqrtf(wave_sum_dpp(q[r]) * (1.f / DM) + 1e-5f);
;         if (MODE == 1) {
; #pragma unroll
;             for (int r = 0; r < NR; ++r) if (lane == r) { stats[2 * row[r]] = mean[r]; stats[2 * row[r] + 1] = rstd[r]; } }
	v_add_f32_dpp v34, v34, v34 row_ror:1 row_mask:0xf bank_mask:0xf bound_ctrl:1
	v_add_f32_dpp v35, v35, v35 row_ror:2 row_mask:0xf bank_mask:0xf bound_ctrl:1
	s_ashr_i32 s25, s24, 31
	v_readlane_b32 s0, v34, 0
	v_add_f32_dpp v35, v35, v35 row_ror:1 row_mask:0xf bank_mask:0xf bound_ctrl:1
	v_readlane_b32 s5, v34, 16
	v_readlane_b32 s2, v35, 0
	v_readlane_b32 s14, v35, 16
	v_readlane_b32 s13, v35, 32
	v_readlane_b32 s15, v35, 48
	v_readlane_b32 s4, v34, 32
	v_readlane_b32 s11, v34, 48
	v_lshl_add_u64 v[34:35], v[66:67], 0, s[28:29]
	s_lshl_b64 s[24:25], s[24:25], 11
	v_mov_b32_e32 v73, v52
	v_mov_b32_e32 v77, v50
	global_load_dwordx4 v[46:49], v[34:35], off nt
	global_load_dwordx4 v[50:53], v[34:35], off offset:1024 nt
	v_lshl_add_u64 v[34:35], v[66:67], 0, s[24:25]
	s_add_i32 s24, s27, s21
	s_cmpk_lt_i32 s24, 0x3e00
	s_cselect_b32 s24, s24, s27
	s_mul_hi_i32 s25, s24, 0x84210843
	s_add_i32 s25, s25, s24
	s_lshr_b32 s27, s25, 31
	s_ashr_i32 s25, s25, 4
	s_add_i32 s25, s25, s27
	s_add_i32 s25, s25, s24
	s_lshl_b32 s24, s25, 1
	s_ashr_i32 s25, s24, 31
	s_lshl_b64 s[28:29], s[24:25], 11
	v_mul_f32_e32 v142, 0x3a800000, v42
	v_lshl_add_u64 v[42:43], v[66:67], 0, s[28:29]
	v_mov_b32_e32 v132, v39
	v_mov_b32_e32 v133, v41
	v_mov_b32_e32 v137, v37
	global_load_dwordx4 v[38:41], v[34:35], off nt
	global_load_dwordx4 v[54:57], v[34:35], off offset:1024 nt
	s_nop 0
	global_load_dwordx4 v[34:37], v[42:43], off nt
	global_load_dwordx4 v[58:61], v[42:43], off offset:1024 nt
	v_mov_b32_e32 v42, s22
	v_mov_b32_e32 v43, s23
	v_add_f32_e32 v42, s6, v42
	v_add_f32_e32 v43, s7, v43
	v_add_f32_e32 v42, v42, v43
	v_fmamk_f32 v42, v42, 0x3a800000, v147
	v_mul_f32_e32 v43, 0x4f800000, v42
	v_cmp_gt_f32_e32 vcc, s26, v42
	s_or_b32 s6, s24, 1
	s_ashr_i32 s7, s6, 31
	v_cndmask_b32_e32 v42, v42, v43, vcc
	v_sqrt_f32_e32 v43, v42
	s_lshl_b64 s[22:23], s[6:7], 11
	v_lshl_add_u64 v[62:63], v[66:67], 0, s[22:23]
	v_mov_b32_e32 v107, v65
	v_add_u32_e32 v44, -1, v43
	v_fma_f32 v45, -v44, v43, v42
	v_cmp_ge_f32_e64 s[6:7], 0, v45
	v_add_u32_e32 v45, 1, v43
	v_mov_b32_e32 v144, s18
	v_cndmask_b32_e64 v44, v43, v44, s[6:7]
	v_fma_f32 v43, -v45, v43, v42
	v_cmp_lt_f32_e64 s[6:7], 0, v43
	v_mov_b32_e32 v146, s19
	v_add_f32_e32 v144, s8, v144
	v_cndmask_b32_e64 v43, v44, v45, s[6:7]
	v_mul_f32_e32 v44, 0x37800000, v43
	v_cndmask_b32_e32 v43, v43, v44, vcc
	v_cmp_class_f32_e32 vcc, v42, v150
	v_add_f32_e32 v146, s9, v146
	v_add_f32_e32 v144, v144, v146
	v_cndmask_b32_e32 v139, v43, v42, vcc
	global_load_dwordx4 v[42:45], v[62:63], off nt
	s_nop 0
	global_load_dwordx4 v[62:65], v[62:63], off offset:1024 nt
	v_div_scale_f32 v113, s[6:7], v139, v139, 1.0
	v_rcp_f32_e32 v141, v113
	v_fmamk_f32 v144, v144, 0x3a800000, v147
	v_mul_f32_e32 v146, 0x4f800000, v144
	v_cmp_gt_f32_e64 s[6:7], s26, v144
	v_fma_f32 v143, -v113, v141, 1.0
	v_fmac_f32_e32 v141, v143, v141
	v_cndmask_b32_e64 v144, v144, v146, s[6:7]
	v_sqrt_f32_e32 v146, v144
	v_div_scale_f32 v143, vcc, 1.0, v139, 1.0
	v_mul_f32_e32 v148, v143, v141
	v_fma_f32 v149, -v113, v148, v143
	v_fmac_f32_e32 v148, v149, v141
	v_add_u32_e32 v149, -1, v146
	v_fma_f32 v151, -v149, v146, v144
	v_cmp_ge_f32_e64 s[8:9], 0, v151
	v_add_u32_e32 v151, 1, v146
	v_fma_f32 v113, -v113, v148, v143
	v_cndmask_b32_e64 v149, v146, v149, s[8:9]
	v_fma_f32 v146, -v151, v146, v144
	v_cmp_lt_f32_e64 s[8:9], 0, v146
	v_mov_b32_e32 v143, s15
	v_add_f32_e32 v143, s13, v143
	v_cndmask_b32_e64 v146, v149, v151, s[8:9]
	v_mul_f32_e32 v149, 0x37800000, v146
	v_cndmask_b32_e64 v146, v146, v149, s[6:7]
	v_cmp_class_f32_e64 s[6:7], v144, v150
	v_div_fmas_f32 v151, v113, v141, v148
	v_mov_b32_e32 v141, s14
	v_cndmask_b32_e64 v149, v146, v144, s[6:7]
	v_div_scale_f32 v144, s[6:7], v149, v149, 1.0
	v_add_f32_e32 v141, s2, v141
	v_rcp_f32_e32 v146, v144
	v_add_f32_e32 v141, v141, v143
	v_fmamk_f32 v141, v141, 0x3a800000, v147
	v_mul_f32_e32 v143, 0x4f800000, v141
	v_cmp_gt_f32_e64 s[6:7], s26, v141
	v_fma_f32 v113, -v144, v146, 1.0
	v_fmac_f32_e32 v146, v113, v146
	v_cndmask_b32_e64 v141, v141, v143, s[6:7]
	v_sqrt_f32_e32 v143, v141
	v_div_scale_f32 v113, vcc, 1.0, v149, 1.0
	v_mul_f32_e32 v148, v113, v146
	v_fma_f32 v152, -v144, v148, v113
	v_fmac_f32_e32 v148, v152, v146
	v_add_u32_e32 v152, -1, v143
	v_fma_f32 v153, -v152, v143, v141
	v_cmp_ge_f32_e64 s[8:9], 0, v153
	v_add_u32_e32 v153, 1, v143
	v_fma_f32 v113, -v144, v148, v113
	v_cndmask_b32_e64 v152, v143, v152, s[8:9]
	v_fma_f32 v143, -v153, v143, v141
	v_cmp_lt_f32_e64 s[8:9], 0, v143
	s_mov_b64 s[14:15], 0
	s_nop 0
	v_cndmask_b32_e64 v143, v152, v153, s[8:9]
	v_mul_f32_e32 v152, 0x37800000, v143
	v_cndmask_b32_e64 v143, v143, v152, s[6:7]
	v_cmp_class_f32_e64 s[6:7], v141, v150
	v_div_fmas_f32 v152, v113, v146, v148
	v_mov_b32_e32 v146, s5
	v_cndmask_b32_e64 v141, v143, v141, s[6:7]
	v_div_scale_f32 v143, s[6:7], v141, v141, 1.0
	v_mov_b32_e32 v148, s11
	v_rcp_f32_e32 v153, v143
	v_add_f32_e32 v146, s0, v146
	v_add_f32_e32 v148, s4, v148
	v_add_f32_e32 v146, v146, v148
	v_fmamk_f32 v146, v146, 0x3a800000, v147
	v_mul_f32_e32 v148, 0x4f800000, v146
	v_cmp_gt_f32_e64 s[6:7], s26, v146
	v_fma_f32 v113, -v143, v153, 1.0
	v_fmac_f32_e32 v153, v113, v153
	v_cndmask_b32_e64 v146, v146, v148, s[6:7]
	v_div_scale_f32 v113, vcc, 1.0, v141, 1.0
	v_sqrt_f32_e32 v148, v146
	v_mul_f32_e32 v144, v113, v153
	v_fma_f32 v154, -v143, v144, v113
	v_fmac_f32_e32 v144, v154, v153
	v_fma_f32 v113, -v143, v144, v113
	v_add_u32_e32 v143, -1, v148
	v_fma_f32 v154, -v143, v148, v146
	v_cmp_ge_f32_e64 s[8:9], 0, v154
	v_add_u32_e32 v154, 1, v148
	v_div_fmas_f32 v113, v113, v153, v144
	v_cndmask_b32_e64 v143, v148, v143, s[8:9]
	v_fma_f32 v148, -v154, v148, v146
	v_cmp_lt_f32_e64 s[8:9], 0, v148
	s_nop 1
	v_cndmask_b32_e64 v143, v143, v154, s[8:9]
	v_mul_f32_e32 v148, 0x37800000, v143
	v_cndmask_b32_e64 v143, v143, v148, s[6:7]
	v_cmp_class_f32_e64 s[6:7], v146, v150
	s_nop 1
	v_cndmask_b32_e64 v143, v143, v146, s[6:7]
	v_div_scale_f32 v148, s[4:5], v143, v143, 1.0
	v_rcp_f32_e32 v154, v148
	v_div_fixup_f32 v146, v113, v141, 1.0
	v_fma_f32 v113, -v148, v154, 1.0
	v_fmac_f32_e32 v154, v113, v154
	v_div_scale_f32 v113, vcc, 1.0, v143, 1.0
	v_mul_f32_e32 v141, v113, v154
	v_fma_f32 v144, -v148, v141, v113
	v_fmac_f32_e32 v141, v144, v154
	v_fma_f32 v113, -v148, v141, v113
	v_div_fmas_f32 v113, v113, v154, v141
	v_div_fixup_f32 v144, v113, v143, 1.0
	v_cmp_lt_i32_e32 vcc, 1, v145
	s_and_saveexec_b64 s[4:5], vcc
	s_xor_b64 s[6:7], exec, s[4:5]
	s_cbranch_execz .LBB0_699
	v_cmp_lt_i32_e32 vcc, 2, v145
	s_mov_b64 s[8:9], 0
	s_and_saveexec_b64 s[4:5], vcc
	s_xor_b64 s[14:15], exec, s[4:5]
	s_cbranch_execz .LBB0_696
	v_cmp_eq_u32_e32 vcc, 3, v145
	s_and_saveexec_b64 s[22:23], vcc
	v_mov_b32_e32 v143, v144
	s_mov_b64 s[8:9], exec
	s_lshl_b32 s0, s10, 1
	v_mov_b64_e32 v[112:113], v[142:143]
	s_or_b64 exec, exec, s[22:23]
	s_and_b64 s[8:9], s[8:9], exec

;     ...
;     if (p0 < p1) {
; #pragma unroll
;         for (int r = 0; r < NR; ++r) { const bf16_t* p = z + (size_t)rowr(p0, r) * DM;
; #pragma unroll
;             for (int j = 0; j < 2; ++j) raw[r][j] = *(const pg8::u32x4*)(p + 8 * lane + 512 * j); } }
;     for (int pi = p0; pi < p1; pi += NP * pstep) {
;         int row[NR];
; #pragma unroll
;         for (int r = 0; r < NR; ++r) row[r] = rowr(pi, r);
;         f32x4 v[NR][4]; float s[NR];
; #pragma unroll
;         for (int r = 0; r < NR; ++r) { s[r] = 0.f;
; #pragma unroll
;             for (int j = 0; j < 2; ++j) {
;                 v[r][2 * j][0] = __builtin_bit_cast(float, raw[r][j].x << 16); v[r][2 * j][1] = __builtin_bit_cast(float, raw[r][j].x & 0xffff0000u);
;                 v[r][2 * j][2] = __builtin_bit_cast(float, raw[r][j].y << 16); v[r][2 * j][3] = __builtin_bit_cast(float, raw[r][j].y & 0xffff0000u);
;                 v[r][2 * j + 1][0] = __builtin_bit_cast(float, raw[r][j].z << 16); v[r][2 * j + 1][1] = __builtin_bit_cast(float, raw[r][j].z & 0xffff0000u);
;                 v[r][2 * j + 1][2] = __builtin_bit_cast(float, raw[r][j].w << 16); v[r][2 * j + 1][3] = __builtin_bit_cast(float, raw[r][j].w & 0xffff0000u); } }
;         { const int nxt = pi + NP * pstep, pq = nxt < p1 ? nxt : pi;
; #pragma unroll
;           for (int r = 0; r < NR; ++r) { const bf16_t* pn = z + (size_t)rowr(pq, r) * DM;
; #pragma unroll
;               for (int j = 0; j < 2; ++j) raw[r][j] = *(const pg8::u32x4*)(pn + 8 * lane + 512 * j); } }
; #pragma unroll
;         for (int r = 0; r < NR; ++r)
; #pragma unroll
;             for (int j = 0; j < 4; ++j) s[r] += (v[r][j][0] + v[r][j][1]) + (v[r][j][2] + v[r][j][3]);
;         float mean[NR], q[NR], rstd[NR];
; #pragma unroll
;         for (int r = 0; r < NR; ++r) { mean[r] = wave_sum_dpp(s[r]) * (1.f / DM); q[r] = 0.f;
; #pragma unroll
;             for (int j = 0; j < 4; ++j) { v[r][j] = v[r][j] - mean[r]; q[r] += (v[r][j][0] * v[r][j][0] + v[r][j][1] * v[r][j][1]) + (v[r][j][2] * v[r][j][2] + v[r][j][3] * v[r][j][3]); } }
; #pragma unroll
;         for (int r = 0; r < NR; ++r) rstd[r] = 1.0f / sqrtf(wave_sum_dpp(q[r]) * (1.f / DM) + 1e-5f);
;         if (MODE == 1) {
; #pragma unroll
;             for (int r = 0; r < NR; ++r) if (lane == r) { stats[2 * row[r]] = mean[r]; stats[2 * row[r] + 1] = rstd[r]; } }
; #pragma unroll
;         for (int j = 0; j < 2; ++j) {
.LBB0_1759:
	s_and_b64 vcc, exec, s[8:9]
	s_cbranch_vccz .LBB0_1779
	v_readlane_b32 s0, v253, 20
	s_add_i32 s0, s0, s6
	s_add_i32 s6, s0, 0xfffffd40
	s_cmpk_gt_i32 s6, 0x3dff
	s_cbranch_scc1 .LBB0_1779
	v_readlane_b32 s0, v253, 4
	v_readlane_b32 s1, v253, 5
	s_load_dwordx4 s[8:11], s[0:1], 0x118
	v_readlane_b32 s0, v253, 27
	s_add_i32 s7, s0, 0xfffffd40
	v_readlane_b32 s0, v253, 21
	s_waitcnt vmcnt(9)
	v_lshlrev_b32_e32 v70, 4, v1
	v_mov_b32_e32 v71, 0
	v_readlane_b32 s1, v253, 22
	s_waitcnt vmcnt(7)
	v_lshlrev_b32_e32 v68, 5, v1
	v_mov_b32_e32 v145, 0x3727c5ac
	v_lshl_add_u64 v[66:67], s[0:1], 0, v[70:71]
	s_mul_hi_i32 s0, s6, 0x84210843
	s_add_i32 s0, s0, s6
	s_lshr_b32 s1, s0, 31
	s_ashr_i32 s0, s0, 4
	s_add_i32 s0, s0, s1
	s_add_i32 s0, s0, s6
	s_lshl_b32 s0, s0, 1
	s_ashr_i32 s1, s0, 31
	s_lshl_b64 s[2:3], s[0:1], 11
	s_or_b32 s0, s0, 1
	s_ashr_i32 s1, s0, 31
	v_lshl_add_u64 v[2:3], v[66:67], 0, s[2:3]
	s_lshl_b64 s[0:1], s[0:1], 11
	global_load_dwordx4 v[46:49], v[2:3], off nt
	global_load_dwordx4 v[50:53], v[2:3], off offset:1024 nt
	v_lshl_add_u64 v[2:3], v[66:67], 0, s[0:1]
	s_add_i32 s0, s6, s7
	s_cmpk_lt_i32 s0, 0x3e00
	s_cselect_b32 s0, s0, s6
	s_mul_hi_i32 s1, s0, 0x84210843
	s_add_i32 s1, s1, s0
	s_lshr_b32 s2, s1, 31
	s_ashr_i32 s1, s1, 4
	s_add_i32 s1, s1, s2
	s_add_i32 s1, s1, s0
	s_lshl_b32 s0, s1, 1
	s_ashr_i32 s1, s0, 31
	s_lshl_b64 s[2:3], s[0:1], 11
	s_or_b32 s0, s0, 1
	s_ashr_i32 s1, s0, 31
	global_load_dwordx4 v[34:37], v[2:3], off nt
	global_load_dwordx4 v[54:57], v[2:3], off offset:1024 nt
	v_lshl_add_u64 v[2:3], v[66:67], 0, s[2:3]
	s_lshl_b64 s[0:1], s[0:1], 11
	global_load_dwordx4 v[38:41], v[2:3], off nt
	global_load_dwordx4 v[58:61], v[2:3], off offset:1024 nt
	v_lshl_add_u64 v[2:3], v[66:67], 0, s[0:1]
	global_load_dwordx4 v[42:45], v[2:3], off nt
	global_load_dwordx4 v[62:65], v[2:3], off offset:1024 nt
	s_waitcnt lgkmcnt(0)
	global_load_dwordx4 v[2:5], v68, s[8:9] offset:16
	global_load_dwordx4 v[6:9], v68, s[10:11] offset:16
	global_load_dwordx4 v[10:13], v68, s[8:9]
	global_load_dwordx4 v[14:17], v68, s[10:11]
	global_load_dwordx4 v[18:21], v68, s[8:9] offset:2064
	global_load_dwordx4 v[22:25], v68, s[10:11] offset:2064
	global_load_dwordx4 v[26:29], v68, s[8:9] offset:2048
	global_load_dwordx4 v[30:33], v68, s[10:11] offset:2048
	v_readlane_b32 s0, v253, 23
	v_readlane_b32 s1, v253, 24
	s_mov_b32 s14, 0xf800000
	v_mov_b32_e32 v147, 0x260
	v_lshl_add_u64 v[68:69], s[0:1], 0, v[70:71]
	v_or_b32_e32 v70, 0x400, v70
	v_lshl_add_u64 v[70:71], s[0:1], 0, v[70:71]
	s_branch .LBB0_1763
.LBB0_1762:
	s_or_b64 exec, exec, s[28:29]
	v_pk_mul_f32 v[106:107], v[106:107], v[142:143] op_sel_hi:[1,0]
	v_pk_mul_f32 v[104:105], v[104:105], v[142:143] op_sel_hi:[1,0]
	v_pk_mul_f32 v[110:111], v[110:111], v[142:143] op_sel_hi:[1,0]
	v_pk_mul_f32 v[108:109], v[108:109], v[142:143] op_sel_hi:[1,0]
	s_ashr_i32 s11, s10, 31
	s_waitcnt vmcnt(12)
	v_pk_fma_f32 v[106:107], v[12:13], v[106:107], v[16:17]
	v_pk_fma_f32 v[104:105], v[10:11], v[104:105], v[14:15]
	v_pk_fma_f32 v[110:111], v[4:5], v[110:111], v[8:9]
	v_pk_fma_f32 v[108:109], v[2:3], v[108:109], v[6:7]
	s_lshl_b64 s[10:11], s[10:11], 11
	v_cvt_pk_bf16_f32 v104, v104, v105
	v_cvt_pk_bf16_f32 v105, v106, v107
	v_cvt_pk_bf16_f32 v106, v108, v109
	v_cvt_pk_bf16_f32 v107, v110, v111
	v_lshl_add_u64 v[108:109], v[68:69], 0, s[10:11]
	global_store_dwordx4 v[108:109], v[104:107], off nt
	v_pk_mul_f32 v[110:111], v[118:119], v[140:141] op_sel_hi:[1,0]
	s_ashr_i32 s9, s8, 31
	v_pk_mul_f32 v[104:105], v[116:117], v[140:141] op_sel_hi:[1,0]
	v_pk_mul_f32 v[106:107], v[114:115], v[140:141] op_sel_hi:[1,0]
	v_pk_fma_f32 v[108:109], v[12:13], v[104:105], v[16:17]
	v_pk_fma_f32 v[104:105], v[10:11], v[106:107], v[14:15]
	v_pk_mul_f32 v[106:107], v[120:121], v[140:141] op_sel_hi:[1,0]
	s_lshl_b64 s[8:9], s[8:9], 11
	v_pk_fma_f32 v[112:113], v[4:5], v[106:107], v[8:9]
	v_pk_fma_f32 v[106:107], v[2:3], v[110:111], v[6:7]
	v_cvt_pk_bf16_f32 v104, v104, v105
	v_cvt_pk_bf16_f32 v105, v108, v109
	v_cvt_pk_bf16_f32 v106, v106, v107
	v_cvt_pk_bf16_f32 v107, v112, v113
	v_lshl_add_u64 v[108:109], v[68:69], 0, s[8:9]
	global_store_dwordx4 v[108:109], v[104:107], off nt
	v_pk_mul_f32 v[110:111], v[126:127], v[146:147] op_sel_hi:[1,0]
	s_ashr_i32 s21, s20, 31
	v_pk_mul_f32 v[104:105], v[124:125], v[146:147] op_sel_hi:[1,0]
	v_pk_mul_f32 v[106:107], v[122:123], v[146:147] op_sel_hi:[1,0]
	v_pk_fma_f32 v[108:109], v[12:13], v[104:105], v[16:17]
	v_pk_fma_f32 v[104:105], v[10:11], v[106:107], v[14:15]
	v_pk_mul_f32 v[106:107], v[128:129], v[146:147] op_sel_hi:[1,0]
	s_lshl_b64 s[20:21], s[20:21], 11
	v_pk_fma_f32 v[112:113], v[4:5], v[106:107], v[8:9]
	v_pk_fma_f32 v[106:107], v[2:3], v[110:111], v[6:7]
	v_cvt_pk_bf16_f32 v104, v104, v105
	v_cvt_pk_bf16_f32 v105, v108, v109
	v_cvt_pk_bf16_f32 v106, v106, v107
	v_cvt_pk_bf16_f32 v107, v112, v113
	v_lshl_add_u64 v[108:109], v[68:69], 0, s[20:21]
	global_store_dwordx4 v[108:109], v[104:107], off nt
	s_add_i32 s0, s6, s7
	v_pk_mul_f32 v[110:111], v[134:135], v[144:145] op_sel_hi:[1,0]
	v_pk_mul_f32 v[104:105], v[132:133], v[144:145] op_sel_hi:[1,0]
	v_pk_mul_f32 v[106:107], v[130:131], v[144:145] op_sel_hi:[1,0]
	v_pk_fma_f32 v[108:109], v[12:13], v[104:105], v[16:17]
	v_pk_fma_f32 v[104:105], v[10:11], v[106:107], v[14:15]
	v_pk_mul_f32 v[106:107], v[136:137], v[144:145] op_sel_hi:[1,0]
	s_ashr_i32 s13, s12, 31
	s_add_i32 s6, s0, s7
	v_pk_fma_f32 v[112:113], v[4:5], v[106:107], v[8:9]
	v_pk_fma_f32 v[106:107], v[2:3], v[110:111], v[6:7]
	s_lshl_b64 s[0:1], s[12:13], 11
	v_cvt_pk_bf16_f32 v104, v104, v105
	v_cvt_pk_bf16_f32 v105, v108, v109
	v_cvt_pk_bf16_f32 v106, v106, v107
	v_cvt_pk_bf16_f32 v107, v112, v113
	v_lshl_add_u64 v[108:109], v[68:69], 0, s[0:1]
	v_pk_mul_f32 v[102:103], v[102:103], v[142:143] op_sel_hi:[1,0]
	v_pk_mul_f32 v[100:101], v[100:101], v[142:143] op_sel_hi:[1,0]
	v_pk_mul_f32 v[98:99], v[98:99], v[142:143] op_sel_hi:[1,0]
	v_pk_mul_f32 v[96:97], v[96:97], v[142:143] op_sel_hi:[1,0]
	global_store_dwordx4 v[108:109], v[104:107], off nt
	s_waitcnt vmcnt(12)
;     ...
;         for (int r = 0; r < NR; ++r) { s[r] = 0.f;
; #pragma unroll
;             for (int j = 0; j < 2; ++j) {
;                 v[r][2 * j][0] = __builtin_bit_cast(float, raw[r][j].x << 16); v[r][2 * j][1] = __builtin_bit_cast(float, raw[r][j].x & 0xffff0000u);
;                 v[r][2 * j][2] = __builtin_bit_cast(float, raw[r][j].y << 16); v[r][2 * j][3] = __builtin_bit_cast(float, raw[r][j].y & 0xffff0000u);
;                 v[r][2 * j + 1][0] = __builtin_bit_cast(float, raw[r][j].z << 16); v[r][2 * j + 1][1] = __builtin_bit_cast(float, raw[r][j].z & 0xffff0000u);
;                 v[r][2 * j + 1][2] = __builtin_bit_cast(float, raw[r][j].w << 16); v[r][2 * j + 1][3] = __builtin_bit_cast(float, raw[r][j].w & 0xffff0000u); } }
;         { const int nxt = pi + NP * pstep, pq = nxt < p1 ? nxt : pi;
; #pragma unroll
;           for (int r = 0; r < NR; ++r) { const bf16_t* pn = z + (size_t)rowr(pq, r) * DM;
; #pragma unroll
;               for (int j = 0; j < 2; ++j) raw[r][j] = *(const pg8::u32x4*)(pn + 8 * lane + 512 * j); } }
; #pragma unroll
;         for (int r = 0; r < NR; ++r)
; #pragma unroll
;             for (int j = 0; j < 4; ++j) s[r] += (v[r][j][0] + v[r][j][1]) + (v[r][j][2] + v[r][j][3]);
;         float mean[NR], q[NR], rstd[NR];
; #pragma unroll
;         for (int r = 0; r < NR; ++r) { mean[r] = wave_sum_dpp(s[r]) * (1.f / DM); q[r] = 0.f;
; #pragma unroll
;             for (int j = 0; j < 4; ++j) { v[r][j] = v[r][j] - mean[r]; q[r] += (v[r][j][0] * v[r][j][0] + v[r][j][1] * v[r][j][1]) + (v[r][j][2] * v[r][j][2] + v[r][j][3] * v[r][j][3]); } }
; #pragma unroll
;         for (int r = 0; r < NR; ++r) rstd[r] = 1.0f / sqrtf(wave_sum_dpp(q[r]) * (1.f / DM) + 1e-5f);
;         if (MODE == 1) {
; #pragma unroll
;             for (int r = 0; r < NR; ++r) if (lane == r) { stats[2 * row[r]] = mean[r]; stats[2 * row[r] + 1] = rstd[r]; } }
; #pragma unroll
;         for (int j = 0; j < 2; ++j) {
;             const int c = 8 * lane + 512 * j;
;             const f32x4 g0 = *(const f32x4*)(g + c), g1 = *(const f32x4*)(g + c + 4), b0 = *(const f32x4*)(b + c), b1 = *(const f32x4*)(b + c + 4);
; #pragma unroll
;             for (int r = 0; r < NR; ++r) {
;                 const f32x4 o0 = v[r][2 * j] * rstd[r] * g0 + b0, o1 = v[r][2 * j + 1] * rstd[r] * g1 + b1;
	v_pk_fma_f32 v[102:103], v[28:29], v[102:103], v[32:33]
	v_pk_fma_f32 v[100:101], v[26:27], v[100:101], v[30:31]
	v_pk_fma_f32 v[104:105], v[20:21], v[98:99], v[24:25]
	v_pk_fma_f32 v[98:99], v[18:19], v[96:97], v[22:23]
	v_cvt_pk_bf16_f32 v96, v100, v101
	v_cvt_pk_bf16_f32 v97, v102, v103
	v_cvt_pk_bf16_f32 v98, v98, v99
	v_cvt_pk_bf16_f32 v99, v104, v105
	v_lshl_add_u64 v[100:101], v[70:71], 0, s[10:11]
	v_pk_mul_f32 v[94:95], v[94:95], v[140:141] op_sel_hi:[1,0]
	v_pk_mul_f32 v[90:91], v[90:91], v[140:141] op_sel_hi:[1,0]
	v_pk_mul_f32 v[92:93], v[92:93], v[140:141] op_sel_hi:[1,0]
	v_pk_mul_f32 v[88:89], v[88:89], v[140:141] op_sel_hi:[1,0]
	global_store_dwordx4 v[100:101], v[96:99], off nt
	v_pk_fma_f32 v[94:95], v[28:29], v[94:95], v[32:33]
	v_pk_fma_f32 v[90:91], v[26:27], v[90:91], v[30:31]
	v_pk_fma_f32 v[92:93], v[20:21], v[92:93], v[24:25]
	v_pk_fma_f32 v[96:97], v[18:19], v[88:89], v[22:23]
	v_cvt_pk_bf16_f32 v88, v90, v91
	v_cvt_pk_bf16_f32 v89, v94, v95
	v_cvt_pk_bf16_f32 v90, v96, v97
	v_cvt_pk_bf16_f32 v91, v92, v93
	v_lshl_add_u64 v[92:93], v[70:71], 0, s[8:9]
	v_pk_mul_f32 v[86:87], v[86:87], v[146:147] op_sel_hi:[1,0]
	v_pk_mul_f32 v[82:83], v[82:83], v[146:147] op_sel_hi:[1,0]
	v_pk_mul_f32 v[84:85], v[84:85], v[146:147] op_sel_hi:[1,0]
	v_pk_mul_f32 v[80:81], v[80:81], v[146:147] op_sel_hi:[1,0]
	global_store_dwordx4 v[92:93], v[88:91], off nt
	v_pk_fma_f32 v[86:87], v[28:29], v[86:87], v[32:33]
	v_pk_fma_f32 v[82:83], v[26:27], v[82:83], v[30:31]
	v_pk_fma_f32 v[84:85], v[20:21], v[84:85], v[24:25]
	v_pk_fma_f32 v[88:89], v[18:19], v[80:81], v[22:23]
	v_cvt_pk_bf16_f32 v80, v82, v83
	v_cvt_pk_bf16_f32 v81, v86, v87
	v_cvt_pk_bf16_f32 v82, v88, v89
	v_cvt_pk_bf16_f32 v83, v84, v85
	v_lshl_add_u64 v[84:85], v[70:71], 0, s[20:21]
	v_pk_mul_f32 v[78:79], v[78:79], v[144:145] op_sel_hi:[1,0]
	v_pk_mul_f32 v[74:75], v[74:75], v[144:145] op_sel_hi:[1,0]
	v_pk_mul_f32 v[76:77], v[76:77], v[144:145] op_sel_hi:[1,0]
	v_pk_mul_f32 v[72:73], v[72:73], v[144:145] op_sel_hi:[1,0]
	global_store_dwordx4 v[84:85], v[80:83], off nt
	v_pk_fma_f32 v[78:79], v[28:29], v[78:79], v[32:33]
	v_pk_fma_f32 v[74:75], v[26:27], v[74:75], v[30:31]
	v_pk_fma_f32 v[76:77], v[20:21], v[76:77], v[24:25]
	v_pk_fma_f32 v[80:81], v[18:19], v[72:73], v[22:23]
	v_cvt_pk_bf16_f32 v72, v74, v75
	v_cvt_pk_bf16_f32 v73, v78, v79
	v_cvt_pk_bf16_f32 v74, v80, v81
	v_cvt_pk_bf16_f32 v75, v76, v77
	v_lshl_add_u64 v[76:77], v[70:71], 0, s[0:1]
	s_cmpk_gt_i32 s6, 0x3dff
	global_store_dwordx4 v[76:77], v[72:75], off nt
	s_cbranch_scc1 .LBB0_1779
.LBB0_1763:
	s_waitcnt vmcnt(13)
	v_lshlrev_b32_e32 v127, 16, v35
	v_lshlrev_b32_e32 v126, 16, v34
	v_and_b32_e32 v129, 0xffff0000, v35
	v_and_b32_e32 v128, 0xffff0000, v34
	v_lshlrev_b32_e32 v100, 16, v50
	v_and_b32_e32 v101, 0xffff0000, v50
	v_lshlrev_b32_e32 v96, 16, v52
	v_and_b32_e32 v116, 0xffff0000, v52
	s_waitcnt vmcnt(8)
	v_lshlrev_b32_e32 v74, 16, v62
	v_and_b32_e32 v75, 0xffff0000, v62
	v_lshlrev_b32_e32 v78, 16, v63
	v_and_b32_e32 v79, 0xffff0000, v63
	v_lshlrev_b32_e32 v72, 16, v64
	v_and_b32_e32 v52, 0xffff0000, v64
	v_lshlrev_b32_e32 v76, 16, v65
	v_and_b32_e32 v50, 0xffff0000, v65
	v_lshlrev_b32_e32 v63, 16, v47
	v_lshlrev_b32_e32 v62, 16, v46
	v_and_b32_e32 v65, 0xffff0000, v47
	v_and_b32_e32 v64, 0xffff0000, v46
	v_pk_add_f32 v[34:35], v[126:127], v[128:129]
	v_pk_add_f32 v[46:47], v[62:63], v[64:65]
	v_add_f32_e32 v34, v34, v35
	v_lshlrev_b32_e32 v131, 16, v37
	v_lshlrev_b32_e32 v130, 16, v36
	v_and_b32_e32 v133, 0xffff0000, v37
	v_and_b32_e32 v132, 0xffff0000, v36
	v_add_f32_e32 v46, v46, v47
	v_lshlrev_b32_e32 v119, 16, v49
	v_lshlrev_b32_e32 v118, 16, v48
	v_and_b32_e32 v121, 0xffff0000, v49
	v_and_b32_e32 v120, 0xffff0000, v48
	v_add_f32_e32 v123, 0, v34
	v_pk_add_f32 v[34:35], v[130:131], v[132:133]
	v_lshlrev_b32_e32 v90, 16, v54
	v_and_b32_e32 v91, 0xffff0000, v54
	v_lshlrev_b32_e32 v94, 16, v55
	v_and_b32_e32 v95, 0xffff0000, v55
	v_add_f32_e32 v115, 0, v46
	v_pk_add_f32 v[46:47], v[118:119], v[120:121]
	v_pk_add_f32 v[34:35], v[34:35], v[34:35] op_sel_hi:[0,1]
	v_lshlrev_b32_e32 v102, 16, v51
	v_and_b32_e32 v103, 0xffff0000, v51
	v_lshlrev_b32_e32 v88, 16, v56
	v_and_b32_e32 v124, 0xffff0000, v56
	v_lshlrev_b32_e32 v92, 16, v57
	v_and_b32_e32 v122, 0xffff0000, v57
	v_pk_add_f32 v[46:47], v[46:47], v[46:47] op_sel_hi:[0,1]
	v_add_f32_e32 v89, v90, v91
	v_add_f32_e32 v125, v94, v95
	v_mov_b32_e32 v93, v35
	v_lshlrev_b32_e32 v98, 16, v53
	v_and_b32_e32 v114, 0xffff0000, v53
	v_add_f32_e32 v97, v100, v101
	v_add_f32_e32 v117, v102, v103
	v_mov_b32_e32 v99, v47
	v_pk_add_f32 v[36:37], v[88:89], v[124:125]
	v_pk_add_f32 v[34:35], v[92:93], v[122:123]
	v_lshlrev_b32_e32 v82, 16, v58
	v_and_b32_e32 v83, 0xffff0000, v58
	v_lshlrev_b32_e32 v86, 16, v59
	v_and_b32_e32 v87, 0xffff0000, v59
	v_lshlrev_b32_e32 v80, 16, v60
	v_and_b32_e32 v56, 0xffff0000, v60
	v_lshlrev_b32_e32 v84, 16, v61
	v_and_b32_e32 v54, 0xffff0000, v61
	v_pk_add_f32 v[48:49], v[96:97], v[116:117]
	v_pk_add_f32 v[46:47], v[98:99], v[114:115]
	v_pk_add_f32 v[34:35], v[36:37], v[34:35]
	v_lshlrev_b32_e32 v59, 16, v39
	v_lshlrev_b32_e32 v58, 16, v38
	v_and_b32_e32 v61, 0xffff0000, v39
	v_and_b32_e32 v60, 0xffff0000, v38
	v_pk_add_f32 v[46:47], v[48:49], v[46:47]
	v_add_f32_e32 v89, v34, v35
	v_pk_add_f32 v[34:35], v[58:59], v[60:61]
	v_add_f32_e32 v97, v46, v47
	v_add_f32_e32 v34, v34, v35
	v_lshlrev_b32_e32 v47, 16, v41
	v_lshlrev_b32_e32 v46, 16, v40
	v_and_b32_e32 v49, 0xffff0000, v41
	v_and_b32_e32 v48, 0xffff0000, v40
	v_add_f32_e32 v55, 0, v34
	v_pk_add_f32 v[34:35], v[46:47], v[48:49]
	v_add_f32_e32 v81, v82, v83
; template <int CTRL> __device__ __forceinline__ float dpp_mov(float x) { return __builtin_bit_cast(float, __builtin_amdgcn_update_dpp(0, __builtin_bit_cast(int, x), CTRL, 0xF, 0xF, true)); }
; __device__ __forceinline__ float rowsum16(float x) { x += dpp_mov<0x128>(x); x += dpp_mov<0x124>(x); x += dpp_mov<0x122>(x); x += dpp_mov<0x121>(x); return x; }
; __device__ __forceinline__ float rl(float x, int l) { return __builtin_bit_cast(float, __builtin_amdgcn_readlane(__builtin_bit_cast(int, x), l)); }
; __device__ __forceinline__ float wave_sum_dpp(float x) { x = rowsum16(x); return (rl(x, 0) + rl(x, 16)) + (rl(x, 32) + rl(x, 48)); }
;     ...
;             for (int j = 0; j < 4; ++j) s[r] += (v[r][j][0] + v[r][j][1]) + (v[r][j][2] + v[r][j][3]);
;         float mean[NR], q[NR], rstd[NR];
; #pragma unroll
;         for (int r = 0; r < NR; ++r) { mean[r] = wave_sum_dpp(s[r]) * (1.f / DM); q[r] = 0.f;
; #pragma unroll
;             for (int j = 0; j < 4; ++j) { v[r][j] = v[r][j] - mean[r]; q[r] += (v[r][j][0] * v[r][j][0] + v[r][j][1] * v[r][j][1]) + (v[r][j][2] * v[r][j][2] + v[r][j][3] * v[r][j][3]); } }
; #pragma unroll
;         for (int r = 0; r < NR; ++r) rstd[r] = 1.0f / sqrtf(wave_sum_dpp(q[r]) * (1.f / DM) + 1e-5f);
	v_pk_add_f32 v[34:35], v[34:35], v[34:35] op_sel_hi:[0,1]
	v_add_f32_e32 v57, v86, v87
	v_mov_b32_e32 v85, v35
	v_pk_add_f32 v[36:37], v[80:81], v[56:57]
	v_pk_add_f32 v[34:35], v[84:85], v[54:55]
	v_lshlrev_b32_e32 v39, 16, v43
	v_pk_add_f32 v[34:35], v[36:37], v[34:35]
	v_lshlrev_b32_e32 v38, 16, v42
	v_and_b32_e32 v41, 0xffff0000, v43
	v_and_b32_e32 v40, 0xffff0000, v42
	v_add_f32_e32 v55, v34, v35
	v_pk_add_f32 v[34:35], v[38:39], v[40:41]
	v_and_b32_e32 v37, 0xffff0000, v45
	v_add_f32_e32 v34, v34, v35
	v_add_f32_e32 v51, 0, v34
	v_lshlrev_b32_e32 v35, 16, v45
	v_lshlrev_b32_e32 v34, 16, v44
	v_and_b32_e32 v36, 0xffff0000, v44
	v_pk_add_f32 v[42:43], v[34:35], v[36:37]
	v_add_f32_e32 v73, v74, v75
	v_pk_add_f32 v[42:43], v[42:43], v[42:43] op_sel_hi:[0,1]
	v_add_f32_e32 v53, v78, v79
	v_mov_b32_e32 v77, v43
	v_pk_add_f32 v[44:45], v[72:73], v[52:53]
	v_pk_add_f32 v[42:43], v[76:77], v[50:51]
	s_nop 0
	v_pk_add_f32 v[42:43], v[44:45], v[42:43]
	s_nop 0
	v_add_f32_e32 v44, v42, v43
	v_add_f32_dpp v42, v97, v97 row_ror:8 row_mask:0xf bank_mask:0xf bound_ctrl:1
	s_nop 1
	v_add_f32_dpp v42, v42, v42 row_ror:4 row_mask:0xf bank_mask:0xf bound_ctrl:1
	s_nop 1
	v_add_f32_dpp v42, v42, v42 row_ror:2 row_mask:0xf bank_mask:0xf bound_ctrl:1
	s_nop 1
	v_add_f32_dpp v42, v42, v42 row_ror:1 row_mask:0xf bank_mask:0xf bound_ctrl:1
	s_nop 0
	v_readlane_b32 s2, v42, 16
	v_readlane_b32 s3, v42, 48
	v_readlane_b32 s0, v42, 0
	v_readlane_b32 s1, v42, 32
	v_mov_b32_e32 v42, s2
	v_mov_b32_e32 v43, s3
	v_pk_add_f32 v[42:43], s[0:1], v[42:43]
	s_nop 0
	v_add_f32_e32 v42, v42, v43
	v_fmac_f32_e32 v65, 0xba800000, v42
	v_fmac_f32_e32 v64, 0xba800000, v42
	v_fmac_f32_e32 v63, 0xba800000, v42
	v_fmac_f32_e32 v62, 0xba800000, v42
	v_mul_f32_e32 v43, v64, v64
	v_mul_f32_e32 v45, v65, v65
	v_fmac_f32_e32 v43, v62, v62
	v_fmac_f32_e32 v45, v63, v63
	v_fmac_f32_e32 v121, 0xba800000, v42
	v_fmac_f32_e32 v120, 0xba800000, v42
	v_add_f32_e32 v43, v43, v45
	v_fmac_f32_e32 v119, 0xba800000, v42
	v_fmac_f32_e32 v118, 0xba800000, v42
	v_mul_f32_e32 v45, v120, v120
	v_mul_f32_e32 v51, v121, v121
	v_fmac_f32_e32 v45, v118, v118
	v_fmac_f32_e32 v51, v119, v119
	v_add_f32_e32 v45, v45, v51
	v_fmac_f32_e32 v103, 0xba800000, v42
	v_fmac_f32_e32 v101, 0xba800000, v42
	v_add_f32_e32 v43, v43, v45
	v_fmac_f32_e32 v102, 0xba800000, v42
	v_fmac_f32_e32 v100, 0xba800000, v42
	v_mul_f32_e32 v45, v101, v101
	v_mul_f32_e32 v51, v103, v103
	v_fmac_f32_e32 v45, v100, v100
	v_fmac_f32_e32 v51, v102, v102
	v_add_f32_e32 v45, v45, v51
	v_fmac_f32_e32 v114, 0xba800000, v42
	v_fmac_f32_e32 v116, 0xba800000, v42
	v_mul_f32_e32 v112, 0x3a800000, v42
	v_add_f32_e32 v43, v45, v43
	v_fmac_f32_e32 v98, 0xba800000, v42
	v_fmac_f32_e32 v96, 0xba800000, v42
	v_mul_f32_e32 v42, v116, v116
	v_mul_f32_e32 v45, v114, v114
	v_fmac_f32_e32 v42, v96, v96
	v_fmac_f32_e32 v45, v98, v98
	v_add_f32_e32 v42, v42, v45
	v_add_f32_e32 v45, v42, v43
	v_mov_b32_e32 v97, v116
	v_add_f32_dpp v42, v89, v89 row_ror:8 row_mask:0xf bank_mask:0xf bound_ctrl:1
	v_mov_b32_e32 v99, v114
	v_mov_b32_e32 v109, v120
	v_add_f32_dpp v42, v42, v42 row_ror:4 row_mask:0xf bank_mask:0xf bound_ctrl:1
	v_mov_b32_e32 v108, v118
	v_mov_b32_e32 v110, v119
	v_add_f32_dpp v42, v42, v42 row_ror:2 row_mask:0xf bank_mask:0xf bound_ctrl:1
	v_mov_b32_e32 v111, v121
	v_mov_b32_e32 v104, v62
	v_add_f32_dpp v42, v42, v42 row_ror:1 row_mask:0xf bank_mask:0xf bound_ctrl:1
	v_mov_b32_e32 v106, v63
	v_readlane_b32 s2, v42, 16
	v_readlane_b32 s3, v42, 48
	v_readlane_b32 s0, v42, 0
	v_readlane_b32 s1, v42, 32
	v_mov_b32_e32 v42, s2
	v_mov_b32_e32 v43, s3
	v_pk_add_f32 v[42:43], s[0:1], v[42:43]
	v_mov_b32_e32 v105, v64
	v_add_f32_e32 v42, v42, v43
	v_fmac_f32_e32 v129, 0xba800000, v42
	v_fmac_f32_e32 v128, 0xba800000, v42
	v_fmac_f32_e32 v127, 0xba800000, v42
	v_fmac_f32_e32 v126, 0xba800000, v42
	v_mul_f32_e32 v43, v128, v128
	v_mul_f32_e32 v51, v129, v129
	v_fmac_f32_e32 v43, v126, v126
	v_fmac_f32_e32 v51, v127, v127
	v_fmac_f32_e32 v133, 0xba800000, v42
	v_fmac_f32_e32 v132, 0xba800000, v42
	v_add_f32_e32 v43, v43, v51
	v_fmac_f32_e32 v131, 0xba800000, v42
	v_fmac_f32_e32 v130, 0xba800000, v42
	v_mul_f32_e32 v51, v132, v132
	v_mul_f32_e32 v53, v133, v133
	v_fmac_f32_e32 v51, v130, v130
	v_fmac_f32_e32 v53, v131, v131
	v_add_f32_e32 v51, v51, v53
	v_fmac_f32_e32 v95, 0xba800000, v42
	v_fmac_f32_e32 v91, 0xba800000, v42
	v_add_f32_e32 v43, v43, v51
	v_fmac_f32_e32 v94, 0xba800000, v42
	v_fmac_f32_e32 v90, 0xba800000, v42
	v_mul_f32_e32 v51, v91, v91
	v_mul_f32_e32 v53, v95, v95
	v_fmac_f32_e32 v51, v90, v90
	v_fmac_f32_e32 v53, v94, v94
	v_add_f32_e32 v51, v51, v53
	v_fmac_f32_e32 v122, 0xba800000, v42
	v_fmac_f32_e32 v124, 0xba800000, v42
	v_mul_f32_e32 v138, 0x3a800000, v42
	v_add_f32_e32 v43, v51, v43
	v_fmac_f32_e32 v92, 0xba800000, v42
	v_fmac_f32_e32 v88, 0xba800000, v42
	v_mul_f32_e32 v42, v124, v124
	v_mul_f32_e32 v51, v122, v122
	v_fmac_f32_e32 v42, v88, v88
	v_fmac_f32_e32 v51, v92, v92
	v_add_f32_e32 v42, v42, v51
	v_add_f32_e32 v51, v42, v43
	v_mov_b32_e32 v116, v127
	v_add_f32_dpp v42, v55, v55 row_ror:8 row_mask:0xf bank_mask:0xf bound_ctrl:1
	v_mov_b32_e32 v114, v126
	v_mov_b32_e32 v115, v128
	v_add_f32_dpp v42, v42, v42 row_ror:4 row_mask:0xf bank_mask:0xf bound_ctrl:1
	v_mov_b32_e32 v120, v131
	v_mov_b32_e32 v118, v130
	v_add_f32_dpp v42, v42, v42 row_ror:2 row_mask:0xf bank_mask:0xf bound_ctrl:1
	v_mov_b32_e32 v119, v132
	v_mov_b32_e32 v117, v129
	v_add_f32_dpp v42, v42, v42 row_ror:1 row_mask:0xf bank_mask:0xf bound_ctrl:1
	v_mov_b32_e32 v121, v133
	v_readlane_b32 s2, v42, 16
	v_readlane_b32 s3, v42, 48
	v_readlane_b32 s0, v42, 0
; __device__ __forceinline__ float wave_sum_dpp(float x) { x = rowsum16(x); return (rl(x, 0) + rl(x, 16)) + (rl(x, 32) + rl(x, 48)); }
;     ...
;         { const int nxt = pi + NP * pstep, pq = nxt < p1 ? nxt : pi;
; #pragma unroll
;           for (int r = 0; r < NR; ++r) { const bf16_t* pn = z + (size_t)rowr(pq, r) * DM;
; #pragma unroll
;               for (int j = 0; j < 2; ++j) raw[r][j] = *(const pg8::u32x4*)(pn + 8 * lane + 512 * j); } }
;     ...
;             for (int j = 0; j < 4; ++j) s[r] += (v[r][j][0] + v[r][j][1]) + (v[r][j][2] + v[r][j][3]);
;         float mean[NR], q[NR], rstd[NR];
; #pragma unroll
;         for (int r = 0; r < NR; ++r) { mean[r] = wave_sum_dpp(s[r]) * (1.f / DM); q[r] = 0.f;
; #pragma unroll
;             for (int j = 0; j < 4; ++j) { v[r][j] = v[r][j] - mean[r]; q[r] += (v[r][j][0] * v[r][j][0] + v[r][j][1] * v[r][j][1]) + (v[r][j][2] * v[r][j][2] + v[r][j][3] * v[r][j][3]); } }
; #pragma unroll
;         for (int r = 0; r < NR; ++r) rstd[r] = 1.0f / sqrtf(wave_sum_dpp(q[r]) * (1.f / DM) + 1e-5f);
	v_readlane_b32 s1, v42, 32
	v_mov_b32_e32 v42, s2
	v_mov_b32_e32 v43, s3
	v_pk_add_f32 v[42:43], s[0:1], v[42:43]
	v_mov_b32_e32 v89, v124
	v_add_f32_e32 v42, v42, v43
	v_fmac_f32_e32 v48, 0xba800000, v42
	v_fmac_f32_e32 v61, 0xba800000, v42
	v_fmac_f32_e32 v60, 0xba800000, v42
	v_fmac_f32_e32 v49, 0xba800000, v42
	v_fmac_f32_e32 v46, 0xba800000, v42
	v_mov_b32_e32 v127, v48
	v_mul_f32_e32 v48, v48, v48
	v_fmac_f32_e32 v59, 0xba800000, v42
	v_fmac_f32_e32 v58, 0xba800000, v42
	v_mul_f32_e32 v43, v60, v60
	v_mul_f32_e32 v53, v61, v61
	v_fmac_f32_e32 v47, 0xba800000, v42
	v_mov_b32_e32 v126, v46
	v_fmac_f32_e32 v48, v46, v46
	v_mul_f32_e32 v46, v49, v49
	v_fmac_f32_e32 v43, v58, v58
	v_fmac_f32_e32 v53, v59, v59
	v_fmac_f32_e32 v46, v47, v47
	v_add_f32_e32 v43, v43, v53
	v_add_f32_e32 v46, v48, v46
	v_fmac_f32_e32 v87, 0xba800000, v42
	v_fmac_f32_e32 v83, 0xba800000, v42
	v_mov_b32_e32 v128, v47
	v_add_f32_e32 v43, v43, v46
	v_fmac_f32_e32 v86, 0xba800000, v42
	v_fmac_f32_e32 v82, 0xba800000, v42
	v_mul_f32_e32 v46, v83, v83
	v_mul_f32_e32 v47, v87, v87
	v_fmac_f32_e32 v46, v82, v82
	v_fmac_f32_e32 v47, v86, v86
	v_add_f32_e32 v46, v46, v47
	v_fmac_f32_e32 v54, 0xba800000, v42
	v_fmac_f32_e32 v56, 0xba800000, v42
	v_mul_f32_e32 v140, 0x3a800000, v42
	v_add_f32_e32 v43, v46, v43
	v_fmac_f32_e32 v84, 0xba800000, v42
	v_fmac_f32_e32 v80, 0xba800000, v42
	v_mul_f32_e32 v42, v56, v56
	v_mul_f32_e32 v46, v54, v54
	v_fmac_f32_e32 v42, v80, v80
	v_fmac_f32_e32 v46, v84, v84
	v_add_f32_e32 v42, v42, v46
	v_add_f32_e32 v46, v42, v43
	v_mov_b32_e32 v93, v122
	v_add_f32_dpp v42, v44, v44 row_ror:8 row_mask:0xf bank_mask:0xf bound_ctrl:1
	v_mov_b32_e32 v122, v58
	v_mov_b32_e32 v123, v60
	v_add_f32_dpp v42, v42, v42 row_ror:4 row_mask:0xf bank_mask:0xf bound_ctrl:1
	v_mov_b32_e32 v124, v59
	v_mov_b32_e32 v125, v61
	v_add_f32_dpp v42, v42, v42 row_ror:2 row_mask:0xf bank_mask:0xf bound_ctrl:1
	v_mov_b32_e32 v129, v49
	v_mov_b32_e32 v81, v56
	v_add_f32_dpp v42, v42, v42 row_ror:1 row_mask:0xf bank_mask:0xf bound_ctrl:1
	v_mov_b32_e32 v85, v54
	v_readlane_b32 s2, v42, 16
	v_readlane_b32 s3, v42, 48
	v_readlane_b32 s0, v42, 0
	v_readlane_b32 s1, v42, 32
	v_mov_b32_e32 v42, s2
	v_mov_b32_e32 v43, s3
	v_pk_add_f32 v[42:43], s[0:1], v[42:43]
	v_readlane_b32 s1, v253, 27
	s_add_i32 s1, s1, s6
	s_addk_i32 s1, 0xfd40
	s_cmpk_lt_i32 s1, 0x3e00
	s_cselect_b32 s1, s1, s6
	s_mul_hi_i32 s12, s1, 0x84210843
	v_add_f32_e32 v42, v42, v43
	s_add_i32 s12, s12, s1
	v_fmac_f32_e32 v36, 0xba800000, v42
	s_lshr_b32 s20, s12, 31
	s_ashr_i32 s12, s12, 4
	v_fmac_f32_e32 v40, 0xba800000, v42
	v_fmac_f32_e32 v37, 0xba800000, v42
	v_fmac_f32_e32 v34, 0xba800000, v42
	v_mov_b32_e32 v135, v36
	v_mul_f32_e32 v36, v36, v36
	s_add_i32 s12, s12, s20
	v_fmac_f32_e32 v41, 0xba800000, v42
	v_fmac_f32_e32 v38, 0xba800000, v42
	v_mov_b32_e32 v131, v40
	v_mul_f32_e32 v40, v40, v40
	v_fmac_f32_e32 v35, 0xba800000, v42
	v_mov_b32_e32 v134, v34
	v_fmac_f32_e32 v36, v34, v34
	v_mul_f32_e32 v34, v37, v37
	s_add_i32 s1, s12, s1
	v_fmac_f32_e32 v39, 0xba800000, v42
	v_mov_b32_e32 v130, v38
	v_fmac_f32_e32 v40, v38, v38
	v_mul_f32_e32 v38, v41, v41
	v_fmac_f32_e32 v34, v35, v35
	v_fmac_f32_e32 v79, 0xba800000, v42
	v_fmac_f32_e32 v75, 0xba800000, v42
	s_lshl_b32 s20, s1, 1
	s_add_i32 s26, s55, s6
	v_fmac_f32_e32 v38, v39, v39
	v_mov_b32_e32 v136, v35
	v_add_f32_e32 v34, v36, v34
	v_fmac_f32_e32 v78, 0xba800000, v42
	v_fmac_f32_e32 v74, 0xba800000, v42
	v_mul_f32_e32 v35, v75, v75
	v_mul_f32_e32 v36, v79, v79
	s_or_b32 s12, s20, 1
	s_addk_i32 s26, 0xfa80
	v_add_f32_e32 v38, v40, v38
	v_fmac_f32_e32 v35, v74, v74
	v_fmac_f32_e32 v36, v78, v78
	s_cmpk_lt_i32 s26, 0x3e00
	v_add_f32_e32 v34, v38, v34
	v_add_f32_e32 v35, v35, v36
	v_fmac_f32_e32 v50, 0xba800000, v42
	v_fmac_f32_e32 v52, 0xba800000, v42
	s_cselect_b32 s30, s26, s6
	v_add_f32_e32 v34, v35, v34
	v_fmac_f32_e32 v76, 0xba800000, v42
	v_fmac_f32_e32 v72, 0xba800000, v42
	v_mul_f32_e32 v35, v52, v52
	v_mul_f32_e32 v36, v50, v50
	s_mul_hi_i32 s26, s30, 0x84210843
	v_fmac_f32_e32 v35, v72, v72
	v_fmac_f32_e32 v36, v76, v76
	s_add_i32 s26, s26, s30
	v_add_f32_e32 v35, v35, v36
	s_lshr_b32 s27, s26, 31
	s_ashr_i32 s26, s26, 4
	v_add_f32_e32 v34, v35, v34
	v_add_f32_dpp v35, v45, v45 row_ror:8 row_mask:0xf bank_mask:0xf bound_ctrl:1
	s_add_i32 s26, s26, s27
	s_add_i32 s26, s26, s30
	v_add_f32_dpp v35, v35, v35 row_ror:4 row_mask:0xf bank_mask:0xf bound_ctrl:1
	s_lshl_b32 s26, s26, 1
	s_ashr_i32 s27, s26, 31
	v_add_f32_dpp v35, v35, v35 row_ror:2 row_mask:0xf bank_mask:0xf bound_ctrl:1
	s_lshl_b64 s[28:29], s[26:27], 11
	s_or_b32 s26, s26, 1
	v_add_f32_dpp v35, v35, v35 row_ror:1 row_mask:0xf bank_mask:0xf bound_ctrl:1
	s_ashr_i32 s27, s26, 31
	v_readlane_b32 s8, v35, 0
	v_readlane_b32 s22, v35, 16
	v_readlane_b32 s9, v35, 32
	v_readlane_b32 s23, v35, 48
	v_add_f32_dpp v35, v51, v51 row_ror:8 row_mask:0xf bank_mask:0xf bound_ctrl:1
	s_lshl_b64 s[26:27], s[26:27], 11
	v_mov_b32_e32 v132, v39
	v_add_f32_dpp v35, v35, v35 row_ror:4 row_mask:0xf bank_mask:0xf bound_ctrl:1
	v_lshl_add_u64 v[38:39], v[66:67], 0, s[26:27]
	s_add_i32 s26, s30, s7
	v_add_f32_dpp v35, v35, v35 row_ror:2 row_mask:0xf bank_mask:0xf bound_ctrl:1
	v_add_f32_dpp v34, v34, v34 row_ror:8 row_mask:0xf bank_mask:0xf bound_ctrl:1
	s_cmpk_lt_i32 s26, 0x3e00
	v_add_f32_dpp v35, v35, v35 row_ror:1 row_mask:0xf bank_mask:0xf bound_ctrl:1
	v_add_f32_dpp v34, v34, v34 row_ror:4 row_mask:0xf bank_mask:0xf bound_ctrl:1
	v_readlane_b32 s10, v35, 0
	v_readlane_b32 s19, v35, 16
	v_readlane_b32 s11, v35, 32
	v_readlane_b32 s21, v35, 48
	v_add_f32_dpp v35, v46, v46 row_ror:8 row_mask:0xf bank_mask:0xf bound_ctrl:1
; __device__ __forceinline__ float wave_sum_dpp(float x) { x = rowsum16(x); return (rl(x, 0) + rl(x, 16)) + (rl(x, 32) + rl(x, 48)); }
;     ...
;         { const int nxt = pi + NP * pstep, pq = nxt < p1 ? nxt : pi;
; #pragma unroll
;           for (int r = 0; r < NR; ++r) { const bf16_t* pn = z + (size_t)rowr(pq, r) * DM;
; #pragma unroll
;               for (int j = 0; j < 2; ++j) raw[r][j] = *(const pg8::u32x4*)(pn + 8 * lane + 512 * j); } }
; #pragma unroll
;         for (int r = 0; r < NR; ++r)
; #pragma unroll
;             for (int j = 0; j < 4; ++j) s[r] += (v[r][j][0] + v[r][j][1]) + (v[r][j][2] + v[r][j][3]);
;         float mean[NR], q[NR], rstd[NR];
; #pragma unroll
;         for (int r = 0; r < NR; ++r) { mean[r] = wave_sum_dpp(s[r]) * (1.f / DM); q[r] = 0.f;
; #pragma unroll
;             for (int j = 0; j < 4; ++j) { v[r][j] = v[r][j] - mean[r]; q[r] += (v[r][j][0] * v[r][j][0] + v[r][j][1] * v[r][j][1]) + (v[r][j][2] * v[r][j][2] + v[r][j][3] * v[r][j][3]); } }
; #pragma unroll
;         for (int r = 0; r < NR; ++r) rstd[r] = 1.0f / sqrtf(wave_sum_dpp(q[r]) * (1.f / DM) + 1e-5f);
;         if (MODE == 1) {
; #pragma unroll
;             for (int r = 0; r < NR; ++r) if (lane == r) { stats[2 * row[r]] = mean[r]; stats[2 * row[r] + 1] = rstd[r]; } }
	s_cselect_b32 s26, s26, s30
	v_add_f32_dpp v34, v34, v34 row_ror:2 row_mask:0xf bank_mask:0xf bound_ctrl:1
	v_add_f32_dpp v35, v35, v35 row_ror:4 row_mask:0xf bank_mask:0xf bound_ctrl:1
	s_mul_hi_i32 s27, s26, 0x84210843
	v_add_f32_dpp v34, v34, v34 row_ror:1 row_mask:0xf bank_mask:0xf bound_ctrl:1
	v_add_f32_dpp v35, v35, v35 row_ror:2 row_mask:0xf bank_mask:0xf bound_ctrl:1
	s_add_i32 s27, s27, s26
	v_readlane_b32 s0, v34, 0
	v_add_f32_dpp v35, v35, v35 row_ror:1 row_mask:0xf bank_mask:0xf bound_ctrl:1
	v_readlane_b32 s5, v34, 16
	v_readlane_b32 s2, v35, 0
	v_readlane_b32 s15, v35, 16
	v_readlane_b32 s3, v35, 32
	v_readlane_b32 s18, v35, 48
	v_readlane_b32 s4, v34, 32
	v_readlane_b32 s13, v34, 48
	v_lshl_add_u64 v[34:35], v[66:67], 0, s[28:29]
	s_lshr_b32 s28, s27, 31
	s_ashr_i32 s27, s27, 4
	s_add_i32 s27, s27, s28
	s_add_i32 s27, s27, s26
	s_lshl_b32 s26, s27, 1
	s_ashr_i32 s27, s26, 31
	s_lshl_b64 s[28:29], s[26:27], 11
	v_mul_f32_e32 v142, 0x3a800000, v42
	v_lshl_add_u64 v[42:43], v[66:67], 0, s[28:29]
	v_mov_b32_e32 v133, v41
	v_mov_b32_e32 v137, v37
	v_mov_b32_e32 v73, v52
	v_mov_b32_e32 v77, v50
	global_load_dwordx4 v[46:49], v[34:35], off nt
	global_load_dwordx4 v[50:53], v[34:35], off offset:1024 nt
	s_nop 0
	global_load_dwordx4 v[34:37], v[38:39], off nt
	global_load_dwordx4 v[54:57], v[38:39], off offset:1024 nt
	s_nop 0
	global_load_dwordx4 v[38:41], v[42:43], off nt
	global_load_dwordx4 v[58:61], v[42:43], off offset:1024 nt
	v_mov_b32_e32 v42, s22
	v_mov_b32_e32 v43, s23
	v_add_f32_e32 v42, s8, v42
	v_add_f32_e32 v43, s9, v43
	v_add_f32_e32 v42, v42, v43
	v_fmamk_f32 v42, v42, 0x3a800000, v145
	v_mul_f32_e32 v43, 0x4f800000, v42
	v_cmp_gt_f32_e32 vcc, s14, v42
	s_or_b32 s8, s26, 1
	s_ashr_i32 s9, s8, 31
	v_cndmask_b32_e32 v42, v42, v43, vcc
	v_sqrt_f32_e32 v43, v42
	s_lshl_b64 s[22:23], s[8:9], 11
	v_lshl_add_u64 v[62:63], v[66:67], 0, s[22:23]
	v_mov_b32_e32 v107, v65
	v_add_u32_e32 v44, -1, v43
	v_fma_f32 v45, -v44, v43, v42
	v_cmp_ge_f32_e64 s[8:9], 0, v45
	v_add_u32_e32 v45, 1, v43
	v_mov_b32_e32 v144, s19
	v_cndmask_b32_e64 v44, v43, v44, s[8:9]
	v_fma_f32 v43, -v45, v43, v42
	v_cmp_lt_f32_e64 s[8:9], 0, v43
	v_mov_b32_e32 v146, s21
	v_add_f32_e32 v144, s10, v144
	v_cndmask_b32_e64 v43, v44, v45, s[8:9]
	v_mul_f32_e32 v44, 0x37800000, v43
	v_cndmask_b32_e32 v43, v43, v44, vcc
	v_cmp_class_f32_e32 vcc, v42, v147
	v_add_f32_e32 v146, s11, v146
	v_add_f32_e32 v144, v144, v146
	v_cndmask_b32_e32 v139, v43, v42, vcc
	global_load_dwordx4 v[42:45], v[62:63], off nt
	s_nop 0
	global_load_dwordx4 v[62:65], v[62:63], off offset:1024 nt
	v_div_scale_f32 v113, s[8:9], v139, v139, 1.0
	v_rcp_f32_e32 v141, v113
	v_fmamk_f32 v144, v144, 0x3a800000, v145
	v_mul_f32_e32 v146, 0x4f800000, v144
	v_cmp_gt_f32_e64 s[8:9], s14, v144
	v_fma_f32 v143, -v113, v141, 1.0
	v_fmac_f32_e32 v141, v143, v141
	v_cndmask_b32_e64 v144, v144, v146, s[8:9]
	v_sqrt_f32_e32 v146, v144
	v_div_scale_f32 v143, vcc, 1.0, v139, 1.0
	v_mul_f32_e32 v148, v143, v141
	v_fma_f32 v149, -v113, v148, v143
	v_fmac_f32_e32 v148, v149, v141
	v_add_u32_e32 v149, -1, v146
	v_fma_f32 v150, -v149, v146, v144
	v_cmp_ge_f32_e64 s[10:11], 0, v150
	v_add_u32_e32 v150, 1, v146
	v_fma_f32 v113, -v113, v148, v143
	v_cndmask_b32_e64 v149, v146, v149, s[10:11]
	v_fma_f32 v146, -v150, v146, v144
	v_cmp_lt_f32_e64 s[10:11], 0, v146
	v_mov_b32_e32 v143, s18
	v_add_f32_e32 v143, s3, v143
	v_cndmask_b32_e64 v146, v149, v150, s[10:11]
	v_mul_f32_e32 v149, 0x37800000, v146
	v_cndmask_b32_e64 v146, v146, v149, s[8:9]
	v_cmp_class_f32_e64 s[8:9], v144, v147
	v_div_fmas_f32 v150, v113, v141, v148
	v_mov_b32_e32 v141, s15
	v_cndmask_b32_e64 v149, v146, v144, s[8:9]
	v_div_scale_f32 v144, s[8:9], v149, v149, 1.0
	v_add_f32_e32 v141, s2, v141
	v_rcp_f32_e32 v146, v144
	v_add_f32_e32 v141, v141, v143
	v_fmamk_f32 v141, v141, 0x3a800000, v145
	v_mul_f32_e32 v143, 0x4f800000, v141
	v_cmp_gt_f32_e64 s[8:9], s14, v141
	v_fma_f32 v113, -v144, v146, 1.0
	v_fmac_f32_e32 v146, v113, v146
	v_cndmask_b32_e64 v141, v141, v143, s[8:9]
	v_sqrt_f32_e32 v143, v141
	v_div_scale_f32 v113, vcc, 1.0, v149, 1.0
	v_mul_f32_e32 v148, v113, v146
	v_fma_f32 v151, -v144, v148, v113
	v_fmac_f32_e32 v148, v151, v146
	v_add_u32_e32 v151, -1, v143
	v_fma_f32 v152, -v151, v143, v141
	v_cmp_ge_f32_e64 s[10:11], 0, v152
	v_add_u32_e32 v152, 1, v143
	v_fma_f32 v113, -v144, v148, v113
	v_cndmask_b32_e64 v151, v143, v151, s[10:11]
	v_fma_f32 v143, -v152, v143, v141
	v_cmp_lt_f32_e64 s[10:11], 0, v143
	s_mov_b64 s[26:27], 0
	s_nop 0
	v_cndmask_b32_e64 v143, v151, v152, s[10:11]
	v_mul_f32_e32 v151, 0x37800000, v143
	v_cndmask_b32_e64 v143, v143, v151, s[8:9]
	v_cmp_class_f32_e64 s[8:9], v141, v147
	v_div_fmas_f32 v151, v113, v146, v148
	v_mov_b32_e32 v146, s5
	v_cndmask_b32_e64 v141, v143, v141, s[8:9]
	v_div_scale_f32 v143, s[2:3], v141, v141, 1.0
	v_mov_b32_e32 v148, s13
	v_rcp_f32_e32 v152, v143
	v_add_f32_e32 v146, s0, v146
	v_add_f32_e32 v148, s4, v148
	v_add_f32_e32 v146, v146, v148
	v_fmamk_f32 v146, v146, 0x3a800000, v145
	v_mul_f32_e32 v148, 0x4f800000, v146
	v_cmp_gt_f32_e64 s[8:9], s14, v146
	v_fma_f32 v113, -v143, v152, 1.0
	v_fmac_f32_e32 v152, v113, v152
	v_cndmask_b32_e64 v146, v146, v148, s[8:9]
	v_div_scale_f32 v113, vcc, 1.0, v141, 1.0
	v_sqrt_f32_e32 v148, v146
	v_mul_f32_e32 v144, v113, v152
	v_fma_f32 v153, -v143, v144, v113
	v_fmac_f32_e32 v144, v153, v152
	v_fma_f32 v113, -v143, v144, v113
	v_add_u32_e32 v143, -1, v148
	v_fma_f32 v153, -v143, v148, v146
	v_cmp_ge_f32_e64 s[10:11], 0, v153
	v_add_u32_e32 v153, 1, v148
	v_div_fmas_f32 v113, v113, v152, v144
	v_cndmask_b32_e64 v143, v148, v143, s[10:11]
	v_fma_f32 v148, -v153, v148, v146
	v_cmp_lt_f32_e64 s[10:11], 0, v148
	s_nop 1
	v_cndmask_b32_e64 v143, v143, v153, s[10:11]
	v_mul_f32_e32 v148, 0x37800000, v143
	v_cndmask_b32_e64 v143, v143, v148, s[8:9]
	v_cmp_class_f32_e64 s[8:9], v146, v147
	s_nop 1
	v_cndmask_b32_e64 v143, v143, v146, s[8:9]
	v_div_scale_f32 v148, s[2:3], v143, v143, 1.0
	v_rcp_f32_e32 v153, v148
	v_div_fixup_f32 v146, v113, v141, 1.0
	v_fma_f32 v113, -v148, v153, 1.0
	v_fmac_f32_e32 v153, v113, v153
	v_div_scale_f32 v113, vcc, 1.0, v143, 1.0
	v_mul_f32_e32 v141, v113, v153
	v_fma_f32 v144, -v148, v141, v113
	v_fmac_f32_e32 v141, v144, v153
	v_fma_f32 v113, -v148, v141, v113
	v_div_fmas_f32 v113, v113, v153, v141
	v_div_fixup_f32 v144, v113, v143, 1.0
	v_cmp_lt_i32_e32 vcc, 1, v1
	s_and_saveexec_b64 s[2:3], vcc
	s_xor_b64 s[8:9], exec, s[2:3]
	s_cbranch_execz .LBB0_1771
	v_cmp_lt_i32_e32 vcc, 2, v1
	s_mov_b64 s[10:11], 0
	s_and_saveexec_b64 s[2:3], vcc
	s_xor_b64 s[26:27], exec, s[2:3]
	s_cbranch_execz .LBB0_1768
	v_cmp_eq_u32_e32 vcc, 3, v1
	s_and_saveexec_b64 s[28:29], vcc
	v_mov_b32_e32 v143, v144
	s_mov_b64 s[10:11], exec
	s_lshl_b32 s0, s12, 1
	v_mov_b64_e32 v[112:113], v[142:143]
	s_or_b64 exec, exec, s[28:29]
	s_and_b64 s[10:11], s[10:11], exec
